# out-proj K loops touch the residual tile (16 lines per wave and iteration, plain dword loads, counted waits +1) so the epilogue reads it from cache
# baseline (speedup 1.0000x reference)
.LBB0_518:
	s_ashr_i32 s19, s18, 31
	s_lshl_b64 s[34:35], s[18:19], 20
	s_add_u32 s34, s56, s34
	s_addc_u32 s35, s57, s35
	s_and_b64 s[6:7], s[6:7], exec
	s_cselect_b32 s19, s35, s41
	s_cselect_b32 s73, s34, s40
	s_add_u32 s74, s40, 0x100
	v_mov_b32_e32 v0, 0
	s_addc_u32 s75, s41, 0
	s_mov_b32 s76, -2
	v_mov_b32_e32 v1, v0
	v_mov_b32_e32 v2, v0
	s_waitcnt lgkmcnt(0)
	v_mov_b32_e32 v3, v0
	v_mov_b32_e32 v4, v0
	v_mov_b32_e32 v5, v0
	v_mov_b32_e32 v6, v0
	v_mov_b32_e32 v7, v0
	v_mov_b32_e32 v16, v0
	v_mov_b32_e32 v17, v0
	v_mov_b32_e32 v18, v0
	v_mov_b32_e32 v19, v0
	v_mov_b32_e32 v20, v0
	v_mov_b32_e32 v21, v0
	v_mov_b32_e32 v22, v0
	v_mov_b32_e32 v23, v0
	v_mov_b32_e32 v32, v0
	v_mov_b32_e32 v33, v0
	v_mov_b32_e32 v34, v0
	v_mov_b32_e32 v35, v0
	v_mov_b32_e32 v36, v0
	v_mov_b32_e32 v37, v0
	v_mov_b32_e32 v38, v0
	v_mov_b32_e32 v39, v0
	v_mov_b32_e32 v44, v0
	v_mov_b32_e32 v45, v0
	v_mov_b32_e32 v46, v0
	v_mov_b32_e32 v47, v0
	v_mov_b32_e32 v48, v0
	v_mov_b32_e32 v49, v0
	v_mov_b32_e32 v50, v0
	v_mov_b32_e32 v51, v0
	v_mov_b32_e32 v8, v0
	v_mov_b32_e32 v9, v0
	v_mov_b32_e32 v10, v0
	v_mov_b32_e32 v11, v0
	v_mov_b32_e32 v12, v0
	v_mov_b32_e32 v13, v0
	v_mov_b32_e32 v14, v0
	v_mov_b32_e32 v15, v0
	v_mov_b32_e32 v24, v0
	v_mov_b32_e32 v25, v0
	v_mov_b32_e32 v26, v0
	v_mov_b32_e32 v27, v0
	v_mov_b32_e32 v28, v0
	v_mov_b32_e32 v29, v0
	v_mov_b32_e32 v30, v0
	v_mov_b32_e32 v31, v0
	v_mov_b32_e32 v40, v0
	v_mov_b32_e32 v41, v0
	v_mov_b32_e32 v42, v0
	v_mov_b32_e32 v43, v0
	v_mov_b32_e32 v52, v0
	v_mov_b32_e32 v53, v0
	v_mov_b32_e32 v54, v0
	v_mov_b32_e32 v55, v0
	v_mov_b32_e32 v56, v0
	v_mov_b32_e32 v57, v0
	v_mov_b32_e32 v58, v0
	v_mov_b32_e32 v59, v0
	v_mov_b32_e32 v60, v0
	v_mov_b32_e32 v61, v0
	v_mov_b32_e32 v62, v0
	v_mov_b32_e32 v63, v0
	v_mov_b32_e32 v64, v0
	v_mov_b32_e32 v65, v0
	v_mov_b32_e32 v66, v0
	v_mov_b32_e32 v67, v0
	v_mov_b32_e32 v68, v0
	v_mov_b32_e32 v69, v0
	v_mov_b32_e32 v70, v0
	v_mov_b32_e32 v71, v0
	v_mov_b32_e32 v80, v0
	v_mov_b32_e32 v81, v0
	v_mov_b32_e32 v82, v0
	v_mov_b32_e32 v83, v0
	v_mov_b32_e32 v84, v0
	v_mov_b32_e32 v85, v0
	v_mov_b32_e32 v86, v0
	v_mov_b32_e32 v87, v0
	v_mov_b32_e32 v96, v0
	v_mov_b32_e32 v97, v0
	v_mov_b32_e32 v98, v0
	v_mov_b32_e32 v99, v0
	v_mov_b32_e32 v100, v0
	v_mov_b32_e32 v101, v0
	v_mov_b32_e32 v102, v0
	v_mov_b32_e32 v103, v0
	v_mov_b32_e32 v108, v0
	v_mov_b32_e32 v109, v0
	v_mov_b32_e32 v110, v0
	v_mov_b32_e32 v111, v0
	v_mov_b32_e32 v112, v0
	v_mov_b32_e32 v113, v0
	v_mov_b32_e32 v114, v0
	v_mov_b32_e32 v115, v0
	v_mov_b32_e32 v72, v0
	v_mov_b32_e32 v73, v0
	v_mov_b32_e32 v74, v0
	v_mov_b32_e32 v75, v0
	v_mov_b32_e32 v76, v0
	v_mov_b32_e32 v77, v0
	v_mov_b32_e32 v78, v0
	v_mov_b32_e32 v79, v0
	v_mov_b32_e32 v88, v0
	v_mov_b32_e32 v89, v0
	v_mov_b32_e32 v90, v0
	v_mov_b32_e32 v91, v0
	v_mov_b32_e32 v92, v0
	v_mov_b32_e32 v93, v0
	v_mov_b32_e32 v94, v0
	v_mov_b32_e32 v95, v0
	v_mov_b32_e32 v104, v0
	v_mov_b32_e32 v105, v0
	v_mov_b32_e32 v106, v0
	v_mov_b32_e32 v107, v0
	v_mov_b32_e32 v116, v0
	v_mov_b32_e32 v117, v0
	v_mov_b32_e32 v118, v0
	v_mov_b32_e32 v119, v0
	v_mov_b32_e32 v120, v0
	v_mov_b32_e32 v121, v0
	v_mov_b32_e32 v122, v0
	v_mov_b32_e32 v123, v0
	v_mov_b32_e32 v124, v0
	v_mov_b32_e32 v125, v0
	v_mov_b32_e32 v126, v0
	v_mov_b32_e32 v127, v0
	v_readlane_b32 s98, v248, 9
	v_readlane_b32 s99, v248, 10
	s_lshl_b32 s100, s71, 21
	s_lshl_b32 s101, s72, 10
	s_add_u32 s100, s100, s101
	s_nop 0
	s_add_u32 s98, s98, s100
	s_addc_u32 s99, s99, 0
	v_mov_b32_e32 v252, s98
	v_mov_b32_e32 v253, s99
	v_lshrrev_b32_e32 v254, 6, v220
	v_lshlrev_b32_e32 v254, 1, v254
	v_bfe_u32 v255, v220, 3, 1
	v_add_u32_e32 v254, v254, v255
	v_lshlrev_b32_e32 v254, 13, v254
	v_and_b32_e32 v255, 7, v220
	v_lshl_add_u32 v254, v255, 7, v254
	v_mov_b32_e32 v255, 0
	v_lshl_add_u64 v[250:251], v[254:255], 0, v[252:253]
	global_load_dword v249, v[250:251], off
.LBB0_519:
	s_add_u32 s6, s38, 0x100
	s_addc_u32 s7, s39, 0
	s_cmp_eq_u32 s76, 28
	s_cselect_b32 s43, s23, s7
	s_cselect_b32 s42, s22, s6
	s_cselect_b32 s41, s19, s75
	s_cselect_b32 s40, s73, s74
	s_add_i32 s77, 0, 0x14000
	v_add_u32_e32 v172, s77, v175
	ds_read_b128 v[128:131], v177
	ds_read_b128 v[132:135], v177 offset:1024
	ds_read_b128 v[136:139], v177 offset:2048
	ds_read_b128 v[140:143], v177 offset:3072
	ds_read_b128 v[144:147], v172
	ds_read_b128 v[164:167], v172 offset:1024
	ds_read_b128 v[168:171], v172 offset:2048
	ds_read_b128 v[180:183], v172 offset:3072
	s_add_i32 m0, s59, 0xc000
	ds_read_b128 v[184:187], v178
	ds_read_b128 v[188:191], v178 offset:1024
	ds_read_b128 v[192:195], v178 offset:2048
	ds_read_b128 v[196:199], v178 offset:3072
	ds_read_b128 v[200:203], v178 offset:4096
	ds_read_b128 v[204:207], v178 offset:5120
	ds_read_b128 v[208:211], v178 offset:6144
	ds_read_b128 v[212:215], v178 offset:7168
	global_load_lds_dwordx4 v158, s[38:39]
	s_add_i32 m0, s59, 0xe000
	s_nop 0
	global_load_lds_dwordx4 v156, s[38:39]
	s_waitcnt vmcnt(9)
	s_waitcnt lgkmcnt(0)
	s_barrier
	s_setprio 1
	s_waitcnt lgkmcnt(0)
	v_mfma_f32_16x16x32_bf16 v[124:127], v[128:131], v[184:187], v[124:127]
	v_mfma_f32_16x16x32_bf16 v[120:123], v[136:139], v[184:187], v[120:123]
	v_mfma_f32_16x16x32_bf16 v[116:119], v[128:131], v[192:195], v[116:119]
	v_mfma_f32_16x16x32_bf16 v[104:107], v[136:139], v[192:195], v[104:107]
	v_mfma_f32_16x16x32_bf16 v[92:95], v[128:131], v[200:203], v[92:95]
	v_mfma_f32_16x16x32_bf16 v[88:91], v[136:139], v[200:203], v[88:91]
	v_mfma_f32_16x16x32_bf16 v[76:79], v[128:131], v[208:211], v[76:79]
	v_mfma_f32_16x16x32_bf16 v[72:75], v[136:139], v[208:211], v[72:75]
	v_mfma_f32_16x16x32_bf16 v[124:127], v[132:135], v[188:191], v[124:127]
	v_mfma_f32_16x16x32_bf16 v[120:123], v[140:143], v[188:191], v[120:123]
	v_mfma_f32_16x16x32_bf16 v[116:119], v[132:135], v[196:199], v[116:119]
	v_mfma_f32_16x16x32_bf16 v[104:107], v[140:143], v[196:199], v[104:107]
	v_mfma_f32_16x16x32_bf16 v[92:95], v[132:135], v[204:207], v[92:95]
	v_mfma_f32_16x16x32_bf16 v[88:91], v[140:143], v[204:207], v[88:91]
	v_mfma_f32_16x16x32_bf16 v[76:79], v[132:135], v[212:215], v[76:79]
	v_mfma_f32_16x16x32_bf16 v[72:75], v[140:143], v[212:215], v[72:75]
	s_setprio 0
	s_setprio 1
	v_mfma_f32_16x16x32_bf16 v[112:115], v[144:147], v[184:187], v[112:115]
	v_mfma_f32_16x16x32_bf16 v[108:111], v[168:171], v[184:187], v[108:111]
	v_mfma_f32_16x16x32_bf16 v[100:103], v[144:147], v[192:195], v[100:103]
	v_mfma_f32_16x16x32_bf16 v[96:99], v[168:171], v[192:195], v[96:99]
	v_mfma_f32_16x16x32_bf16 v[84:87], v[144:147], v[200:203], v[84:87]
	v_mfma_f32_16x16x32_bf16 v[80:83], v[168:171], v[200:203], v[80:83]
	v_mfma_f32_16x16x32_bf16 v[68:71], v[144:147], v[208:211], v[68:71]
	v_mfma_f32_16x16x32_bf16 v[64:67], v[168:171], v[208:211], v[64:67]
	v_mfma_f32_16x16x32_bf16 v[112:115], v[164:167], v[188:191], v[112:115]
	v_mfma_f32_16x16x32_bf16 v[108:111], v[180:183], v[188:191], v[108:111]
	v_mfma_f32_16x16x32_bf16 v[100:103], v[164:167], v[196:199], v[100:103]
	v_mfma_f32_16x16x32_bf16 v[96:99], v[180:183], v[196:199], v[96:99]
	v_mfma_f32_16x16x32_bf16 v[84:87], v[164:167], v[204:207], v[84:87]
	v_mfma_f32_16x16x32_bf16 v[80:83], v[180:183], v[204:207], v[80:83]
	v_mfma_f32_16x16x32_bf16 v[68:71], v[164:167], v[212:215], v[68:71]
	v_mfma_f32_16x16x32_bf16 v[64:67], v[180:183], v[212:215], v[64:67]
	s_setprio 0
	s_barrier
	s_add_i32 s38, s67, s58
	s_mov_b64 s[98:99], s[40:41]
	s_mov_b32 m0, s38
	ds_read_b128 v[184:187], v178 offset:16384
	ds_read_b128 v[188:191], v178 offset:17408
	ds_read_b128 v[192:195], v178 offset:18432
	ds_read_b128 v[196:199], v178 offset:19456
	ds_read_b128 v[200:203], v178 offset:20480
	ds_read_b128 v[204:207], v178 offset:21504
	ds_read_b128 v[208:211], v178 offset:22528
	ds_read_b128 v[212:215], v178 offset:23552
	global_load_lds_dwordx4 v150, s[40:41]
	s_add_i32 m0, s38, 0x2000
	s_add_u32 s38, s40, 0x80000
	s_addc_u32 s39, s41, 0
	s_add_i32 s77, s77, s58
	global_load_lds_dwordx4 v154, s[40:41]
	s_mov_b32 m0, s77
	s_mov_b64 s[100:101], s[42:43]
	global_load_lds_dwordx4 v150, s[38:39]
	s_add_i32 m0, s77, 0x2000
	s_nop 0
	global_load_lds_dwordx4 v154, s[38:39]
	s_mov_b32 m0, s59
	s_nop 0
	global_load_lds_dwordx4 v148, s[42:43]
	s_mov_b32 m0, s60
	s_nop 0
	global_load_lds_dwordx4 v152, s[42:43]
	s_waitcnt vmcnt(9)
	s_waitcnt lgkmcnt(0)
	s_barrier
	s_setprio 1
	s_waitcnt lgkmcnt(0)
	v_mfma_f32_16x16x32_bf16 v[60:63], v[128:131], v[184:187], v[60:63]
	v_mfma_f32_16x16x32_bf16 v[56:59], v[136:139], v[184:187], v[56:59]
	v_mfma_f32_16x16x32_bf16 v[52:55], v[128:131], v[192:195], v[52:55]
	v_mfma_f32_16x16x32_bf16 v[40:43], v[136:139], v[192:195], v[40:43]
	v_mfma_f32_16x16x32_bf16 v[28:31], v[128:131], v[200:203], v[28:31]
	v_mfma_f32_16x16x32_bf16 v[24:27], v[136:139], v[200:203], v[24:27]
	v_mfma_f32_16x16x32_bf16 v[12:15], v[128:131], v[208:211], v[12:15]
	v_mfma_f32_16x16x32_bf16 v[8:11], v[136:139], v[208:211], v[8:11]
	v_mfma_f32_16x16x32_bf16 v[60:63], v[132:135], v[188:191], v[60:63]
	v_mfma_f32_16x16x32_bf16 v[56:59], v[140:143], v[188:191], v[56:59]
	v_mfma_f32_16x16x32_bf16 v[52:55], v[132:135], v[196:199], v[52:55]
	v_mfma_f32_16x16x32_bf16 v[40:43], v[140:143], v[196:199], v[40:43]
	v_mfma_f32_16x16x32_bf16 v[28:31], v[132:135], v[204:207], v[28:31]
	v_mfma_f32_16x16x32_bf16 v[24:27], v[140:143], v[204:207], v[24:27]
	v_mfma_f32_16x16x32_bf16 v[12:15], v[132:135], v[212:215], v[12:15]
	v_mfma_f32_16x16x32_bf16 v[8:11], v[140:143], v[212:215], v[8:11]
	s_setprio 0
	s_setprio 1
	v_mfma_f32_16x16x32_bf16 v[48:51], v[144:147], v[184:187], v[48:51]
	v_mfma_f32_16x16x32_bf16 v[44:47], v[168:171], v[184:187], v[44:47]
	v_mfma_f32_16x16x32_bf16 v[36:39], v[144:147], v[192:195], v[36:39]
	v_mfma_f32_16x16x32_bf16 v[32:35], v[168:171], v[192:195], v[32:35]
	v_mfma_f32_16x16x32_bf16 v[20:23], v[144:147], v[200:203], v[20:23]
	v_mfma_f32_16x16x32_bf16 v[16:19], v[168:171], v[200:203], v[16:19]
	v_mfma_f32_16x16x32_bf16 v[4:7], v[144:147], v[208:211], v[4:7]
	v_mfma_f32_16x16x32_bf16 v[0:3], v[168:171], v[208:211], v[0:3]
	v_mfma_f32_16x16x32_bf16 v[48:51], v[164:167], v[188:191], v[48:51]
	v_mfma_f32_16x16x32_bf16 v[44:47], v[180:183], v[188:191], v[44:47]
	v_mfma_f32_16x16x32_bf16 v[36:39], v[164:167], v[196:199], v[36:39]
	v_mfma_f32_16x16x32_bf16 v[32:35], v[180:183], v[196:199], v[32:35]
	v_mfma_f32_16x16x32_bf16 v[20:23], v[164:167], v[204:207], v[20:23]
	v_mfma_f32_16x16x32_bf16 v[16:19], v[180:183], v[204:207], v[16:19]
	v_mfma_f32_16x16x32_bf16 v[4:7], v[164:167], v[212:215], v[4:7]
	v_mfma_f32_16x16x32_bf16 v[0:3], v[180:183], v[212:215], v[0:3]
	s_setprio 0
	s_barrier
	s_add_i32 s77, 0, 0x18000
	s_add_i32 s78, 0, 0x1c000
	v_add_u32_e32 v140, s77, v175
	v_add_u32_e32 v180, s78, v175
	ds_read_b128 v[128:131], v140
	ds_read_b128 v[132:135], v140 offset:1024
	ds_read_b128 v[136:139], v140 offset:2048
	ds_read_b128 v[140:143], v140 offset:3072
	ds_read_b128 v[144:147], v180
	ds_read_b128 v[164:167], v180 offset:1024
	ds_read_b128 v[168:171], v180 offset:2048
	ds_read_b128 v[180:183], v180 offset:3072
	s_add_u32 s38, s42, 0x140000
	s_addc_u32 s39, s43, 0
	s_mov_b32 m0, s61
	ds_read_b128 v[184:187], v178 offset:32768
	ds_read_b128 v[188:191], v178 offset:33792
	ds_read_b128 v[192:195], v178 offset:34816
	ds_read_b128 v[196:199], v178 offset:35840
	ds_read_b128 v[200:203], v178 offset:36864
	ds_read_b128 v[204:207], v178 offset:37888
	ds_read_b128 v[208:211], v178 offset:38912
	ds_read_b128 v[212:215], v178 offset:39936
	global_load_lds_dwordx4 v148, s[38:39]
	s_mov_b32 m0, s62
	s_nop 0
	global_load_lds_dwordx4 v152, s[38:39]
	s_waitcnt vmcnt(8)
	s_waitcnt lgkmcnt(0)
	s_barrier
	s_setprio 1
	s_waitcnt lgkmcnt(0)
	v_mfma_f32_16x16x32_bf16 v[124:127], v[128:131], v[184:187], v[124:127]
	v_mfma_f32_16x16x32_bf16 v[120:123], v[136:139], v[184:187], v[120:123]
	v_mfma_f32_16x16x32_bf16 v[116:119], v[128:131], v[192:195], v[116:119]
	v_mfma_f32_16x16x32_bf16 v[104:107], v[136:139], v[192:195], v[104:107]
	v_mfma_f32_16x16x32_bf16 v[92:95], v[128:131], v[200:203], v[92:95]
	v_mfma_f32_16x16x32_bf16 v[88:91], v[136:139], v[200:203], v[88:91]
	v_mfma_f32_16x16x32_bf16 v[76:79], v[128:131], v[208:211], v[76:79]
	v_mfma_f32_16x16x32_bf16 v[72:75], v[136:139], v[208:211], v[72:75]
	v_mfma_f32_16x16x32_bf16 v[124:127], v[132:135], v[188:191], v[124:127]
	v_mfma_f32_16x16x32_bf16 v[120:123], v[140:143], v[188:191], v[120:123]
	v_mfma_f32_16x16x32_bf16 v[116:119], v[132:135], v[196:199], v[116:119]
	v_mfma_f32_16x16x32_bf16 v[104:107], v[140:143], v[196:199], v[104:107]
	v_mfma_f32_16x16x32_bf16 v[92:95], v[132:135], v[204:207], v[92:95]
	v_mfma_f32_16x16x32_bf16 v[88:91], v[140:143], v[204:207], v[88:91]
	v_mfma_f32_16x16x32_bf16 v[76:79], v[132:135], v[212:215], v[76:79]
	v_mfma_f32_16x16x32_bf16 v[72:75], v[140:143], v[212:215], v[72:75]
	s_setprio 0
	s_setprio 1
	v_mfma_f32_16x16x32_bf16 v[112:115], v[144:147], v[184:187], v[112:115]
	v_mfma_f32_16x16x32_bf16 v[108:111], v[168:171], v[184:187], v[108:111]
	v_mfma_f32_16x16x32_bf16 v[100:103], v[144:147], v[192:195], v[100:103]
	v_mfma_f32_16x16x32_bf16 v[96:99], v[168:171], v[192:195], v[96:99]
	v_mfma_f32_16x16x32_bf16 v[84:87], v[144:147], v[200:203], v[84:87]
	v_mfma_f32_16x16x32_bf16 v[80:83], v[168:171], v[200:203], v[80:83]
	v_mfma_f32_16x16x32_bf16 v[68:71], v[144:147], v[208:211], v[68:71]
	v_mfma_f32_16x16x32_bf16 v[64:67], v[168:171], v[208:211], v[64:67]
	v_mfma_f32_16x16x32_bf16 v[112:115], v[164:167], v[188:191], v[112:115]
	v_mfma_f32_16x16x32_bf16 v[108:111], v[180:183], v[188:191], v[108:111]
	v_mfma_f32_16x16x32_bf16 v[100:103], v[164:167], v[196:199], v[100:103]
	v_mfma_f32_16x16x32_bf16 v[96:99], v[180:183], v[196:199], v[96:99]
	v_mfma_f32_16x16x32_bf16 v[84:87], v[164:167], v[204:207], v[84:87]
	v_mfma_f32_16x16x32_bf16 v[80:83], v[180:183], v[204:207], v[80:83]
	v_mfma_f32_16x16x32_bf16 v[68:71], v[164:167], v[212:215], v[68:71]
	v_mfma_f32_16x16x32_bf16 v[64:67], v[180:183], v[212:215], v[64:67]
	s_setprio 0
	s_barrier
	s_add_i32 s38, s77, s58
	s_add_i32 m0, s38, 0xffffff80
	ds_read_b128 v[184:187], v178 offset:49152
	ds_read_b128 v[188:191], v178 offset:50176
	ds_read_b128 v[192:195], v178 offset:51200
	ds_read_b128 v[196:199], v178 offset:52224
	ds_read_b128 v[200:203], v178 offset:53248
	ds_read_b128 v[204:207], v178 offset:54272
	ds_read_b128 v[208:211], v178 offset:55296
	ds_read_b128 v[212:215], v178 offset:56320
	global_load_lds_dwordx4 v150, s[98:99] offset:128
	s_add_i32 m0, s38, 0x1f80
	s_add_u32 s38, s40, 0x80080
	s_addc_u32 s39, s41, 0
	s_add_i32 s40, s78, s58
	global_load_lds_dwordx4 v154, s[98:99] offset:128
	s_mov_b32 m0, s40
	s_nop 0
	global_load_lds_dwordx4 v150, s[38:39]
	s_add_i32 m0, s40, 0x2000
	s_nop 0
	global_load_lds_dwordx4 v154, s[38:39]
	s_add_i32 m0, s64, 0xffffff80
	s_nop 0
	global_load_lds_dwordx4 v148, s[100:101] offset:128
	s_add_i32 m0, s65, 0xffffff80
	s_nop 0
	global_load_lds_dwordx4 v152, s[100:101] offset:128
	v_add_u32_e32 v254, 0x20000, v254
	v_and_b32_e32 v254, 0x1fffff, v254
	v_lshl_add_u64 v[250:251], v[254:255], 0, v[252:253]
	global_load_dword v249, v[250:251], off
	s_waitcnt vmcnt(9)
	s_waitcnt lgkmcnt(0)
	s_barrier
	s_setprio 1
	s_waitcnt lgkmcnt(0)
	v_mfma_f32_16x16x32_bf16 v[60:63], v[128:131], v[184:187], v[60:63]
	v_mfma_f32_16x16x32_bf16 v[56:59], v[136:139], v[184:187], v[56:59]
	v_mfma_f32_16x16x32_bf16 v[52:55], v[128:131], v[192:195], v[52:55]
	v_mfma_f32_16x16x32_bf16 v[40:43], v[136:139], v[192:195], v[40:43]
	v_mfma_f32_16x16x32_bf16 v[28:31], v[128:131], v[200:203], v[28:31]
	v_mfma_f32_16x16x32_bf16 v[24:27], v[136:139], v[200:203], v[24:27]
	v_mfma_f32_16x16x32_bf16 v[12:15], v[128:131], v[208:211], v[12:15]
	v_mfma_f32_16x16x32_bf16 v[8:11], v[136:139], v[208:211], v[8:11]
	v_mfma_f32_16x16x32_bf16 v[60:63], v[132:135], v[188:191], v[60:63]
	v_mfma_f32_16x16x32_bf16 v[56:59], v[140:143], v[188:191], v[56:59]
	v_mfma_f32_16x16x32_bf16 v[52:55], v[132:135], v[196:199], v[52:55]
	v_mfma_f32_16x16x32_bf16 v[40:43], v[140:143], v[196:199], v[40:43]
	v_mfma_f32_16x16x32_bf16 v[28:31], v[132:135], v[204:207], v[28:31]
	v_mfma_f32_16x16x32_bf16 v[24:27], v[140:143], v[204:207], v[24:27]
	v_mfma_f32_16x16x32_bf16 v[12:15], v[132:135], v[212:215], v[12:15]
	v_mfma_f32_16x16x32_bf16 v[8:11], v[140:143], v[212:215], v[8:11]
	s_setprio 0
	s_setprio 1
	v_mfma_f32_16x16x32_bf16 v[48:51], v[144:147], v[184:187], v[48:51]
	v_mfma_f32_16x16x32_bf16 v[44:47], v[168:171], v[184:187], v[44:47]
	v_mfma_f32_16x16x32_bf16 v[36:39], v[144:147], v[192:195], v[36:39]
	v_mfma_f32_16x16x32_bf16 v[32:35], v[168:171], v[192:195], v[32:35]
	v_mfma_f32_16x16x32_bf16 v[20:23], v[144:147], v[200:203], v[20:23]
	v_mfma_f32_16x16x32_bf16 v[16:19], v[168:171], v[200:203], v[16:19]
	v_mfma_f32_16x16x32_bf16 v[4:7], v[144:147], v[208:211], v[4:7]
	v_mfma_f32_16x16x32_bf16 v[0:3], v[168:171], v[208:211], v[0:3]
	v_mfma_f32_16x16x32_bf16 v[48:51], v[164:167], v[188:191], v[48:51]
	v_mfma_f32_16x16x32_bf16 v[44:47], v[180:183], v[188:191], v[44:47]
	v_mfma_f32_16x16x32_bf16 v[36:39], v[164:167], v[196:199], v[36:39]
	v_mfma_f32_16x16x32_bf16 v[32:35], v[180:183], v[196:199], v[32:35]
	v_mfma_f32_16x16x32_bf16 v[20:23], v[164:167], v[204:207], v[20:23]
	v_mfma_f32_16x16x32_bf16 v[16:19], v[180:183], v[204:207], v[16:19]
	v_mfma_f32_16x16x32_bf16 v[4:7], v[164:167], v[212:215], v[4:7]
	v_mfma_f32_16x16x32_bf16 v[0:3], v[180:183], v[212:215], v[0:3]
	s_setprio 0
	s_barrier
	s_add_i32 s76, s76, 2
	s_add_u32 s74, s74, 0x100
	s_addc_u32 s75, s75, 0
	s_cmp_gt_u32 s76, 29
	s_mov_b64 s[38:39], s[6:7]
	s_cbranch_scc0 .LBB0_519
	s_and_b64 vcc, exec, s[16:17]
	s_cbranch_vccz .LBB0_522
	s_barrier

.LBB0_991:
	s_ashr_i32 s19, s18, 31
	s_lshl_b64 s[22:23], s[18:19], 22
	s_add_u32 s22, s56, s22
	s_addc_u32 s23, s57, s23
	s_and_b64 s[34:35], s[4:5], exec
	s_cselect_b32 s19, s23, s41
	s_cselect_b32 s71, s22, s40
	s_ashr_i32 s17, s16, 31
	s_lshl_b64 s[34:35], s[16:17], 20
	s_add_u32 s34, s58, s34
	s_addc_u32 s35, s59, s35
	s_and_b64 s[52:53], s[4:5], exec
	s_cselect_b32 s17, s35, s43
	s_cselect_b32 s72, s34, s42
	s_add_u32 s40, s40, 0x200080
	s_addc_u32 s41, s41, 0
	s_add_u32 s73, s42, 0x100
	v_mov_b32_e32 v0, 0
	s_addc_u32 s74, s43, 0
	s_mov_b32 s75, -2
	v_mov_b32_e32 v1, v0
	v_mov_b32_e32 v2, v0
	s_waitcnt lgkmcnt(0)
	v_mov_b32_e32 v3, v0
	v_mov_b32_e32 v4, v0
	v_mov_b32_e32 v5, v0
	v_mov_b32_e32 v6, v0
	v_mov_b32_e32 v7, v0
	v_mov_b32_e32 v16, v0
	v_mov_b32_e32 v17, v0
	v_mov_b32_e32 v18, v0
	v_mov_b32_e32 v19, v0
	v_mov_b32_e32 v20, v0
	v_mov_b32_e32 v21, v0
	v_mov_b32_e32 v22, v0
	v_mov_b32_e32 v23, v0
	s_waitcnt vmcnt(0)
	v_mov_b32_e32 v32, v0
	v_mov_b32_e32 v33, v0
	v_mov_b32_e32 v34, v0
	v_mov_b32_e32 v35, v0
	v_mov_b32_e32 v36, v0
	v_mov_b32_e32 v37, v0
	v_mov_b32_e32 v38, v0
	v_mov_b32_e32 v39, v0
	v_mov_b32_e32 v44, v0
	v_mov_b32_e32 v45, v0
	v_mov_b32_e32 v46, v0
	v_mov_b32_e32 v47, v0
	v_mov_b32_e32 v48, v0
	v_mov_b32_e32 v49, v0
	v_mov_b32_e32 v50, v0
	v_mov_b32_e32 v51, v0
	v_mov_b32_e32 v8, v0
	v_mov_b32_e32 v9, v0
	v_mov_b32_e32 v10, v0
	v_mov_b32_e32 v11, v0
	v_mov_b32_e32 v12, v0
	v_mov_b32_e32 v13, v0
	v_mov_b32_e32 v14, v0
	v_mov_b32_e32 v15, v0
	v_mov_b32_e32 v24, v0
	v_mov_b32_e32 v25, v0
	v_mov_b32_e32 v26, v0
	v_mov_b32_e32 v27, v0
	v_mov_b32_e32 v28, v0
	v_mov_b32_e32 v29, v0
	v_mov_b32_e32 v30, v0
	v_mov_b32_e32 v31, v0
	v_mov_b32_e32 v40, v0
	v_mov_b32_e32 v41, v0
	v_mov_b32_e32 v42, v0
	v_mov_b32_e32 v43, v0
	v_mov_b32_e32 v52, v0
	v_mov_b32_e32 v53, v0
	v_mov_b32_e32 v54, v0
	v_mov_b32_e32 v55, v0
	v_mov_b32_e32 v56, v0
	v_mov_b32_e32 v57, v0
	v_mov_b32_e32 v58, v0
	v_mov_b32_e32 v59, v0
	v_mov_b32_e32 v60, v0
	v_mov_b32_e32 v61, v0
	v_mov_b32_e32 v62, v0
	v_mov_b32_e32 v63, v0
	v_mov_b32_e32 v64, v0
	v_mov_b32_e32 v65, v0
	v_mov_b32_e32 v66, v0
	v_mov_b32_e32 v67, v0
	v_mov_b32_e32 v68, v0
	v_mov_b32_e32 v69, v0
	v_mov_b32_e32 v70, v0
	v_mov_b32_e32 v71, v0
	v_mov_b32_e32 v80, v0
	v_mov_b32_e32 v81, v0
	v_mov_b32_e32 v82, v0
	v_mov_b32_e32 v83, v0
	v_mov_b32_e32 v84, v0
	v_mov_b32_e32 v85, v0
	v_mov_b32_e32 v86, v0
	v_mov_b32_e32 v87, v0
	v_mov_b32_e32 v96, v0
	v_mov_b32_e32 v97, v0
	v_mov_b32_e32 v98, v0
	v_mov_b32_e32 v99, v0
	v_mov_b32_e32 v100, v0
	v_mov_b32_e32 v101, v0
	v_mov_b32_e32 v102, v0
	v_mov_b32_e32 v103, v0
	v_mov_b32_e32 v108, v0
	v_mov_b32_e32 v109, v0
	v_mov_b32_e32 v110, v0
	v_mov_b32_e32 v111, v0
	v_mov_b32_e32 v112, v0
	v_mov_b32_e32 v113, v0
	v_mov_b32_e32 v114, v0
	v_mov_b32_e32 v115, v0
	v_mov_b32_e32 v72, v0
	v_mov_b32_e32 v73, v0
	v_mov_b32_e32 v74, v0
	v_mov_b32_e32 v75, v0
	v_mov_b32_e32 v76, v0
	v_mov_b32_e32 v77, v0
	v_mov_b32_e32 v78, v0
	v_mov_b32_e32 v79, v0
	v_mov_b32_e32 v88, v0
	v_mov_b32_e32 v89, v0
	v_mov_b32_e32 v90, v0
	v_mov_b32_e32 v91, v0
	v_mov_b32_e32 v92, v0
	v_mov_b32_e32 v93, v0
	v_mov_b32_e32 v94, v0
	v_mov_b32_e32 v95, v0
	v_mov_b32_e32 v104, v0
	v_mov_b32_e32 v105, v0
	v_mov_b32_e32 v106, v0
	v_mov_b32_e32 v107, v0
	v_mov_b32_e32 v116, v0
	v_mov_b32_e32 v117, v0
	v_mov_b32_e32 v118, v0
	v_mov_b32_e32 v119, v0
	v_mov_b32_e32 v120, v0
	v_mov_b32_e32 v121, v0
	v_mov_b32_e32 v122, v0
	v_mov_b32_e32 v123, v0
	v_mov_b32_e32 v124, v0
	v_mov_b32_e32 v125, v0
	v_mov_b32_e32 v126, v0
	v_mov_b32_e32 v127, v0
	v_readlane_b32 s98, v248, 6
	v_readlane_b32 s99, v248, 7
	s_lshl_b32 s100, s38, 21
	s_lshl_b32 s101, s39, 10
	s_add_u32 s100, s100, s101
	s_nop 0
	s_add_u32 s98, s98, s100
	s_addc_u32 s99, s99, 0
	v_mov_b32_e32 v252, s98
	v_mov_b32_e32 v253, s99
	v_lshrrev_b32_e32 v254, 6, v220
	v_lshlrev_b32_e32 v254, 1, v254
	v_bfe_u32 v255, v220, 3, 1
	v_add_u32_e32 v254, v254, v255
	v_lshlrev_b32_e32 v254, 13, v254
	v_and_b32_e32 v255, 7, v220
	v_lshl_add_u32 v254, v255, 7, v254
	v_mov_b32_e32 v255, 0
	v_lshl_add_u64 v[250:251], v[254:255], 0, v[252:253]
	global_load_dword v249, v[250:251], off
.LBB0_992:
	ds_read_b128 v[128:131], v183
	ds_read_b128 v[132:135], v183 offset:1024
	ds_read_b128 v[136:139], v183 offset:2048
	ds_read_b128 v[140:143], v183 offset:3072
	ds_read_b128 v[144:147], v184
	ds_read_b128 v[164:167], v184 offset:1024
	ds_read_b128 v[168:171], v184 offset:2048
	ds_read_b128 v[172:175], v184 offset:3072
	s_add_u32 s42, s40, 0xffe00080
	s_addc_u32 s43, s41, -1
	s_cmp_eq_u32 s75, 28
	s_cselect_b32 s53, s19, s43
	s_cselect_b32 s52, s71, s42
	s_cselect_b32 s43, s17, s74
	s_cselect_b32 s42, s72, s73
	s_add_i32 m0, s61, 0xc000
	ds_read_b128 v[176:179], v185
	ds_read_b128 v[188:191], v185 offset:1024
	ds_read_b128 v[192:195], v185 offset:2048
	ds_read_b128 v[196:199], v185 offset:3072
	ds_read_b128 v[200:203], v185 offset:4096
	ds_read_b128 v[204:207], v185 offset:5120
	ds_read_b128 v[208:211], v185 offset:6144
	ds_read_b128 v[212:215], v185 offset:7168
	global_load_lds_dwordx4 v158, s[40:41]
	s_add_i32 m0, s61, 0xe000
	s_nop 0
	global_load_lds_dwordx4 v156, s[40:41]
	s_waitcnt vmcnt(9)
	s_waitcnt lgkmcnt(0)
	s_barrier
	s_setprio 1
	s_waitcnt lgkmcnt(0)
	v_mfma_f32_16x16x32_bf16 v[124:127], v[128:131], v[176:179], v[124:127]
	v_mfma_f32_16x16x32_bf16 v[120:123], v[136:139], v[176:179], v[120:123]
	v_mfma_f32_16x16x32_bf16 v[116:119], v[128:131], v[192:195], v[116:119]
	v_mfma_f32_16x16x32_bf16 v[104:107], v[136:139], v[192:195], v[104:107]
	v_mfma_f32_16x16x32_bf16 v[92:95], v[128:131], v[200:203], v[92:95]
	v_mfma_f32_16x16x32_bf16 v[88:91], v[136:139], v[200:203], v[88:91]
	v_mfma_f32_16x16x32_bf16 v[76:79], v[128:131], v[208:211], v[76:79]
	v_mfma_f32_16x16x32_bf16 v[72:75], v[136:139], v[208:211], v[72:75]
	v_mfma_f32_16x16x32_bf16 v[124:127], v[132:135], v[188:191], v[124:127]
	v_mfma_f32_16x16x32_bf16 v[120:123], v[140:143], v[188:191], v[120:123]
	v_mfma_f32_16x16x32_bf16 v[116:119], v[132:135], v[196:199], v[116:119]
	v_mfma_f32_16x16x32_bf16 v[104:107], v[140:143], v[196:199], v[104:107]
	v_mfma_f32_16x16x32_bf16 v[92:95], v[132:135], v[204:207], v[92:95]
	v_mfma_f32_16x16x32_bf16 v[88:91], v[140:143], v[204:207], v[88:91]
	v_mfma_f32_16x16x32_bf16 v[76:79], v[132:135], v[212:215], v[76:79]
	v_mfma_f32_16x16x32_bf16 v[72:75], v[140:143], v[212:215], v[72:75]
	s_setprio 0
	s_setprio 1
	v_mfma_f32_16x16x32_bf16 v[112:115], v[144:147], v[176:179], v[112:115]
	v_mfma_f32_16x16x32_bf16 v[108:111], v[168:171], v[176:179], v[108:111]
	v_mfma_f32_16x16x32_bf16 v[100:103], v[144:147], v[192:195], v[100:103]
	v_mfma_f32_16x16x32_bf16 v[96:99], v[168:171], v[192:195], v[96:99]
	v_mfma_f32_16x16x32_bf16 v[84:87], v[144:147], v[200:203], v[84:87]
	v_mfma_f32_16x16x32_bf16 v[80:83], v[168:171], v[200:203], v[80:83]
	v_mfma_f32_16x16x32_bf16 v[68:71], v[144:147], v[208:211], v[68:71]
	v_mfma_f32_16x16x32_bf16 v[64:67], v[168:171], v[208:211], v[64:67]
	v_mfma_f32_16x16x32_bf16 v[112:115], v[164:167], v[188:191], v[112:115]
	v_mfma_f32_16x16x32_bf16 v[108:111], v[172:175], v[188:191], v[108:111]
	v_mfma_f32_16x16x32_bf16 v[100:103], v[164:167], v[196:199], v[100:103]
	v_mfma_f32_16x16x32_bf16 v[96:99], v[172:175], v[196:199], v[96:99]
	v_mfma_f32_16x16x32_bf16 v[84:87], v[164:167], v[204:207], v[84:87]
	v_mfma_f32_16x16x32_bf16 v[80:83], v[172:175], v[204:207], v[80:83]
	v_mfma_f32_16x16x32_bf16 v[68:71], v[164:167], v[212:215], v[68:71]
	v_mfma_f32_16x16x32_bf16 v[64:67], v[172:175], v[212:215], v[64:67]
	s_setprio 0
	s_barrier
	s_add_i32 s76, s69, s60
	s_mov_b64 s[98:99], s[42:43]
	s_mov_b32 m0, s76
	ds_read_b128 v[176:179], v185 offset:16384
	ds_read_b128 v[188:191], v185 offset:17408
	ds_read_b128 v[192:195], v185 offset:18432
	ds_read_b128 v[196:199], v185 offset:19456
	ds_read_b128 v[200:203], v185 offset:20480
	ds_read_b128 v[204:207], v185 offset:21504
	ds_read_b128 v[208:211], v185 offset:22528
	ds_read_b128 v[212:215], v185 offset:23552
	global_load_lds_dwordx4 v150, s[42:43]
	s_add_i32 m0, s76, 0x2000
	s_add_u32 s76, s42, 0x80000
	s_addc_u32 s77, s43, 0
	s_add_i32 s78, s70, s60
	global_load_lds_dwordx4 v154, s[42:43]
	s_mov_b32 m0, s78
	s_mov_b64 s[100:101], s[52:53]
	global_load_lds_dwordx4 v150, s[76:77]
	s_add_i32 m0, s78, 0x2000
	s_nop 0
	global_load_lds_dwordx4 v154, s[76:77]
	s_mov_b32 m0, s61
	s_nop 0
	global_load_lds_dwordx4 v148, s[52:53]
	s_mov_b32 m0, s62
	s_nop 0
	global_load_lds_dwordx4 v152, s[52:53]
	s_waitcnt vmcnt(9)
	s_waitcnt lgkmcnt(0)
	s_barrier
	s_setprio 1
	s_waitcnt lgkmcnt(0)
	v_mfma_f32_16x16x32_bf16 v[60:63], v[128:131], v[176:179], v[60:63]
	v_mfma_f32_16x16x32_bf16 v[56:59], v[136:139], v[176:179], v[56:59]
	v_mfma_f32_16x16x32_bf16 v[52:55], v[128:131], v[192:195], v[52:55]
	v_mfma_f32_16x16x32_bf16 v[40:43], v[136:139], v[192:195], v[40:43]
	v_mfma_f32_16x16x32_bf16 v[28:31], v[128:131], v[200:203], v[28:31]
	v_mfma_f32_16x16x32_bf16 v[24:27], v[136:139], v[200:203], v[24:27]
	v_mfma_f32_16x16x32_bf16 v[12:15], v[128:131], v[208:211], v[12:15]
	v_mfma_f32_16x16x32_bf16 v[8:11], v[136:139], v[208:211], v[8:11]
	v_mfma_f32_16x16x32_bf16 v[60:63], v[132:135], v[188:191], v[60:63]
	v_mfma_f32_16x16x32_bf16 v[56:59], v[140:143], v[188:191], v[56:59]
	v_mfma_f32_16x16x32_bf16 v[52:55], v[132:135], v[196:199], v[52:55]
	v_mfma_f32_16x16x32_bf16 v[40:43], v[140:143], v[196:199], v[40:43]
	v_mfma_f32_16x16x32_bf16 v[28:31], v[132:135], v[204:207], v[28:31]
	v_mfma_f32_16x16x32_bf16 v[24:27], v[140:143], v[204:207], v[24:27]
	v_mfma_f32_16x16x32_bf16 v[12:15], v[132:135], v[212:215], v[12:15]
	v_mfma_f32_16x16x32_bf16 v[8:11], v[140:143], v[212:215], v[8:11]
	s_setprio 0
	s_setprio 1
	v_mfma_f32_16x16x32_bf16 v[48:51], v[144:147], v[176:179], v[48:51]
	v_mfma_f32_16x16x32_bf16 v[44:47], v[168:171], v[176:179], v[44:47]
	v_mfma_f32_16x16x32_bf16 v[36:39], v[144:147], v[192:195], v[36:39]
	v_mfma_f32_16x16x32_bf16 v[32:35], v[168:171], v[192:195], v[32:35]
	v_mfma_f32_16x16x32_bf16 v[20:23], v[144:147], v[200:203], v[20:23]
	v_mfma_f32_16x16x32_bf16 v[16:19], v[168:171], v[200:203], v[16:19]
	v_mfma_f32_16x16x32_bf16 v[4:7], v[144:147], v[208:211], v[4:7]
	v_mfma_f32_16x16x32_bf16 v[0:3], v[168:171], v[208:211], v[0:3]
	v_mfma_f32_16x16x32_bf16 v[48:51], v[164:167], v[188:191], v[48:51]
	v_mfma_f32_16x16x32_bf16 v[44:47], v[172:175], v[188:191], v[44:47]
	v_mfma_f32_16x16x32_bf16 v[36:39], v[164:167], v[196:199], v[36:39]
	v_mfma_f32_16x16x32_bf16 v[32:35], v[172:175], v[196:199], v[32:35]
	v_mfma_f32_16x16x32_bf16 v[20:23], v[164:167], v[204:207], v[20:23]
	v_mfma_f32_16x16x32_bf16 v[16:19], v[172:175], v[204:207], v[16:19]
	v_mfma_f32_16x16x32_bf16 v[4:7], v[164:167], v[212:215], v[4:7]
	v_mfma_f32_16x16x32_bf16 v[0:3], v[172:175], v[212:215], v[0:3]
	s_setprio 0
	s_barrier
	s_add_i32 s76, 0, 0x18000
	s_add_i32 s77, 0, 0x1c000
	v_add_u32_e32 v140, s76, v181
	v_add_u32_e32 v172, s77, v181
	ds_read_b128 v[128:131], v140
	ds_read_b128 v[132:135], v140 offset:1024
	ds_read_b128 v[136:139], v140 offset:2048
	ds_read_b128 v[140:143], v140 offset:3072
	ds_read_b128 v[144:147], v172
	ds_read_b128 v[164:167], v172 offset:1024
	ds_read_b128 v[168:171], v172 offset:2048
	ds_read_b128 v[172:175], v172 offset:3072
	s_add_u32 s52, s52, 0x200000
	s_addc_u32 s53, s53, 0
	s_mov_b32 m0, s63
	ds_read_b128 v[176:179], v185 offset:32768
	ds_read_b128 v[188:191], v185 offset:33792
	ds_read_b128 v[192:195], v185 offset:34816
	ds_read_b128 v[196:199], v185 offset:35840
	ds_read_b128 v[200:203], v185 offset:36864
	ds_read_b128 v[204:207], v185 offset:37888
	ds_read_b128 v[208:211], v185 offset:38912
	ds_read_b128 v[212:215], v185 offset:39936
	global_load_lds_dwordx4 v148, s[52:53]
	s_mov_b32 m0, s64
	s_nop 0
	global_load_lds_dwordx4 v152, s[52:53]
	s_waitcnt vmcnt(8)
	s_waitcnt lgkmcnt(0)
	s_barrier
	s_setprio 1
	s_waitcnt lgkmcnt(0)
	v_mfma_f32_16x16x32_bf16 v[124:127], v[128:131], v[176:179], v[124:127]
	v_mfma_f32_16x16x32_bf16 v[120:123], v[136:139], v[176:179], v[120:123]
	v_mfma_f32_16x16x32_bf16 v[116:119], v[128:131], v[192:195], v[116:119]
	v_mfma_f32_16x16x32_bf16 v[104:107], v[136:139], v[192:195], v[104:107]
	v_mfma_f32_16x16x32_bf16 v[92:95], v[128:131], v[200:203], v[92:95]
	v_mfma_f32_16x16x32_bf16 v[88:91], v[136:139], v[200:203], v[88:91]
	v_mfma_f32_16x16x32_bf16 v[76:79], v[128:131], v[208:211], v[76:79]
	v_mfma_f32_16x16x32_bf16 v[72:75], v[136:139], v[208:211], v[72:75]
	v_mfma_f32_16x16x32_bf16 v[124:127], v[132:135], v[188:191], v[124:127]
	v_mfma_f32_16x16x32_bf16 v[120:123], v[140:143], v[188:191], v[120:123]
	v_mfma_f32_16x16x32_bf16 v[116:119], v[132:135], v[196:199], v[116:119]
	v_mfma_f32_16x16x32_bf16 v[104:107], v[140:143], v[196:199], v[104:107]
	v_mfma_f32_16x16x32_bf16 v[92:95], v[132:135], v[204:207], v[92:95]
	v_mfma_f32_16x16x32_bf16 v[88:91], v[140:143], v[204:207], v[88:91]
	v_mfma_f32_16x16x32_bf16 v[76:79], v[132:135], v[212:215], v[76:79]
	v_mfma_f32_16x16x32_bf16 v[72:75], v[140:143], v[212:215], v[72:75]
	s_setprio 0
	s_setprio 1
	v_mfma_f32_16x16x32_bf16 v[112:115], v[144:147], v[176:179], v[112:115]
	v_mfma_f32_16x16x32_bf16 v[108:111], v[168:171], v[176:179], v[108:111]
	v_mfma_f32_16x16x32_bf16 v[100:103], v[144:147], v[192:195], v[100:103]
	v_mfma_f32_16x16x32_bf16 v[96:99], v[168:171], v[192:195], v[96:99]
	v_mfma_f32_16x16x32_bf16 v[84:87], v[144:147], v[200:203], v[84:87]
	v_mfma_f32_16x16x32_bf16 v[80:83], v[168:171], v[200:203], v[80:83]
	v_mfma_f32_16x16x32_bf16 v[68:71], v[144:147], v[208:211], v[68:71]
	v_mfma_f32_16x16x32_bf16 v[64:67], v[168:171], v[208:211], v[64:67]
	v_mfma_f32_16x16x32_bf16 v[112:115], v[164:167], v[188:191], v[112:115]
	v_mfma_f32_16x16x32_bf16 v[108:111], v[172:175], v[188:191], v[108:111]
	v_mfma_f32_16x16x32_bf16 v[100:103], v[164:167], v[196:199], v[100:103]
	v_mfma_f32_16x16x32_bf16 v[96:99], v[172:175], v[196:199], v[96:99]
	v_mfma_f32_16x16x32_bf16 v[84:87], v[164:167], v[204:207], v[84:87]
	v_mfma_f32_16x16x32_bf16 v[80:83], v[172:175], v[204:207], v[80:83]
	v_mfma_f32_16x16x32_bf16 v[68:71], v[164:167], v[212:215], v[68:71]
	v_mfma_f32_16x16x32_bf16 v[64:67], v[172:175], v[212:215], v[64:67]
	s_setprio 0
	s_barrier
	s_add_i32 s52, s76, s60
	s_add_i32 m0, s52, 0xffffff80
	ds_read_b128 v[176:179], v185 offset:49152
	ds_read_b128 v[188:191], v185 offset:50176
	ds_read_b128 v[192:195], v185 offset:51200
	ds_read_b128 v[196:199], v185 offset:52224
	ds_read_b128 v[200:203], v185 offset:53248
	ds_read_b128 v[204:207], v185 offset:54272
	ds_read_b128 v[208:211], v185 offset:55296
	ds_read_b128 v[212:215], v185 offset:56320
	global_load_lds_dwordx4 v150, s[98:99] offset:128
	s_add_i32 m0, s52, 0x1f80
	s_add_u32 s42, s42, 0x80080
	s_addc_u32 s43, s43, 0
	s_add_i32 s52, s77, s60
	global_load_lds_dwordx4 v154, s[98:99] offset:128
	s_mov_b32 m0, s52
	s_nop 0
	global_load_lds_dwordx4 v150, s[42:43]
	s_add_i32 m0, s52, 0x2000
	s_nop 0
	global_load_lds_dwordx4 v154, s[42:43]
	s_add_i32 m0, s66, 0xffffff80
	s_nop 0
	global_load_lds_dwordx4 v148, s[100:101] offset:128
	s_add_i32 m0, s67, 0xffffff80
	s_nop 0
	global_load_lds_dwordx4 v152, s[100:101] offset:128
	v_add_u32_e32 v254, 0x20000, v254
	v_and_b32_e32 v254, 0x1fffff, v254
	v_lshl_add_u64 v[250:251], v[254:255], 0, v[252:253]
	global_load_dword v249, v[250:251], off
	s_waitcnt vmcnt(9)
	s_waitcnt lgkmcnt(0)
	s_barrier
	s_setprio 1
	s_waitcnt lgkmcnt(0)
	v_mfma_f32_16x16x32_bf16 v[60:63], v[128:131], v[176:179], v[60:63]
	v_mfma_f32_16x16x32_bf16 v[56:59], v[136:139], v[176:179], v[56:59]
	v_mfma_f32_16x16x32_bf16 v[52:55], v[128:131], v[192:195], v[52:55]
	v_mfma_f32_16x16x32_bf16 v[40:43], v[136:139], v[192:195], v[40:43]
	v_mfma_f32_16x16x32_bf16 v[28:31], v[128:131], v[200:203], v[28:31]
	v_mfma_f32_16x16x32_bf16 v[24:27], v[136:139], v[200:203], v[24:27]
	v_mfma_f32_16x16x32_bf16 v[12:15], v[128:131], v[208:211], v[12:15]
	v_mfma_f32_16x16x32_bf16 v[8:11], v[136:139], v[208:211], v[8:11]
	v_mfma_f32_16x16x32_bf16 v[60:63], v[132:135], v[188:191], v[60:63]
	v_mfma_f32_16x16x32_bf16 v[56:59], v[140:143], v[188:191], v[56:59]
	v_mfma_f32_16x16x32_bf16 v[52:55], v[132:135], v[196:199], v[52:55]
	v_mfma_f32_16x16x32_bf16 v[40:43], v[140:143], v[196:199], v[40:43]
	v_mfma_f32_16x16x32_bf16 v[28:31], v[132:135], v[204:207], v[28:31]
	v_mfma_f32_16x16x32_bf16 v[24:27], v[140:143], v[204:207], v[24:27]
	v_mfma_f32_16x16x32_bf16 v[12:15], v[132:135], v[212:215], v[12:15]
	v_mfma_f32_16x16x32_bf16 v[8:11], v[140:143], v[212:215], v[8:11]
	s_setprio 0
	s_setprio 1
	v_mfma_f32_16x16x32_bf16 v[48:51], v[144:147], v[176:179], v[48:51]
	v_mfma_f32_16x16x32_bf16 v[44:47], v[168:171], v[176:179], v[44:47]
	v_mfma_f32_16x16x32_bf16 v[36:39], v[144:147], v[192:195], v[36:39]
	v_mfma_f32_16x16x32_bf16 v[32:35], v[168:171], v[192:195], v[32:35]
	v_mfma_f32_16x16x32_bf16 v[20:23], v[144:147], v[200:203], v[20:23]
	v_mfma_f32_16x16x32_bf16 v[16:19], v[168:171], v[200:203], v[16:19]
	v_mfma_f32_16x16x32_bf16 v[4:7], v[144:147], v[208:211], v[4:7]
	v_mfma_f32_16x16x32_bf16 v[0:3], v[168:171], v[208:211], v[0:3]
	v_mfma_f32_16x16x32_bf16 v[48:51], v[164:167], v[188:191], v[48:51]
	v_mfma_f32_16x16x32_bf16 v[44:47], v[172:175], v[188:191], v[44:47]
	v_mfma_f32_16x16x32_bf16 v[36:39], v[164:167], v[196:199], v[36:39]
	v_mfma_f32_16x16x32_bf16 v[32:35], v[172:175], v[196:199], v[32:35]
	v_mfma_f32_16x16x32_bf16 v[20:23], v[164:167], v[204:207], v[20:23]
	v_mfma_f32_16x16x32_bf16 v[16:19], v[172:175], v[204:207], v[16:19]
	v_mfma_f32_16x16x32_bf16 v[4:7], v[164:167], v[212:215], v[4:7]
	v_mfma_f32_16x16x32_bf16 v[0:3], v[172:175], v[212:215], v[0:3]
	s_setprio 0
	s_barrier
	s_add_i32 s75, s75, 2
	s_add_u32 s40, s40, 0x100
	s_addc_u32 s41, s41, 0
	s_add_u32 s73, s73, 0x100
	s_addc_u32 s74, s74, 0
	s_cmp_gt_u32 s75, 29
	s_cbranch_scc0 .LBB0_992
	s_and_b64 vcc, exec, s[14:15]
	s_cbranch_vccz .LBB0_995
	s_barrier

.LBB0_1472:
	s_ashr_i32 s19, s18, 31
	s_lshl_b64 s[34:35], s[18:19], 20
	s_add_u32 s34, s54, s34
	s_addc_u32 s35, s55, s35
	s_and_b64 s[6:7], s[6:7], exec
	s_cselect_b32 s19, s35, s39
	s_cselect_b32 s69, s34, s38
	s_add_u32 s70, s38, 0x100
	v_mov_b32_e32 v0, 0
	s_addc_u32 s71, s39, 0
	s_mov_b32 s72, -2
	v_mov_b32_e32 v1, v0
	v_mov_b32_e32 v2, v0
	s_waitcnt lgkmcnt(0)
	v_mov_b32_e32 v3, v0
	v_mov_b32_e32 v4, v0
	v_mov_b32_e32 v5, v0
	v_mov_b32_e32 v6, v0
	v_mov_b32_e32 v7, v0
	v_mov_b32_e32 v16, v0
	v_mov_b32_e32 v17, v0
	v_mov_b32_e32 v18, v0
	v_mov_b32_e32 v19, v0
	v_mov_b32_e32 v20, v0
	v_mov_b32_e32 v21, v0
	v_mov_b32_e32 v22, v0
	v_mov_b32_e32 v23, v0
	s_waitcnt vmcnt(0)
	v_mov_b32_e32 v32, v0
	v_mov_b32_e32 v33, v0
	v_mov_b32_e32 v34, v0
	v_mov_b32_e32 v35, v0
	v_mov_b32_e32 v36, v0
	v_mov_b32_e32 v37, v0
	v_mov_b32_e32 v38, v0
	v_mov_b32_e32 v39, v0
	v_mov_b32_e32 v44, v0
	v_mov_b32_e32 v45, v0
	v_mov_b32_e32 v46, v0
	v_mov_b32_e32 v47, v0
	v_mov_b32_e32 v48, v0
	v_mov_b32_e32 v49, v0
	v_mov_b32_e32 v50, v0
	v_mov_b32_e32 v51, v0
	v_mov_b32_e32 v8, v0
	v_mov_b32_e32 v9, v0
	v_mov_b32_e32 v10, v0
	v_mov_b32_e32 v11, v0
	v_mov_b32_e32 v12, v0
	v_mov_b32_e32 v13, v0
	v_mov_b32_e32 v14, v0
	v_mov_b32_e32 v15, v0
	v_mov_b32_e32 v24, v0
	v_mov_b32_e32 v25, v0
	v_mov_b32_e32 v26, v0
	v_mov_b32_e32 v27, v0
	v_mov_b32_e32 v28, v0
	v_mov_b32_e32 v29, v0
	v_mov_b32_e32 v30, v0
	v_mov_b32_e32 v31, v0
	v_mov_b32_e32 v40, v0
	v_mov_b32_e32 v41, v0
	v_mov_b32_e32 v42, v0
	v_mov_b32_e32 v43, v0
	v_mov_b32_e32 v52, v0
	v_mov_b32_e32 v53, v0
	v_mov_b32_e32 v54, v0
	v_mov_b32_e32 v55, v0
	v_mov_b32_e32 v56, v0
	v_mov_b32_e32 v57, v0
	v_mov_b32_e32 v58, v0
	v_mov_b32_e32 v59, v0
	v_mov_b32_e32 v60, v0
	v_mov_b32_e32 v61, v0
	v_mov_b32_e32 v62, v0
	v_mov_b32_e32 v63, v0
	v_mov_b32_e32 v64, v0
	v_mov_b32_e32 v65, v0
	v_mov_b32_e32 v66, v0
	v_mov_b32_e32 v67, v0
	v_mov_b32_e32 v68, v0
	v_mov_b32_e32 v69, v0
	v_mov_b32_e32 v70, v0
	v_mov_b32_e32 v71, v0
	v_mov_b32_e32 v80, v0
	v_mov_b32_e32 v81, v0
	v_mov_b32_e32 v82, v0
	v_mov_b32_e32 v83, v0
	v_mov_b32_e32 v84, v0
	v_mov_b32_e32 v85, v0
	v_mov_b32_e32 v86, v0
	v_mov_b32_e32 v87, v0
	v_mov_b32_e32 v96, v0
	v_mov_b32_e32 v97, v0
	v_mov_b32_e32 v98, v0
	v_mov_b32_e32 v99, v0
	v_mov_b32_e32 v100, v0
	v_mov_b32_e32 v101, v0
	v_mov_b32_e32 v102, v0
	v_mov_b32_e32 v103, v0
	v_mov_b32_e32 v108, v0
	v_mov_b32_e32 v109, v0
	v_mov_b32_e32 v110, v0
	v_mov_b32_e32 v111, v0
	v_mov_b32_e32 v112, v0
	v_mov_b32_e32 v113, v0
	v_mov_b32_e32 v114, v0
	v_mov_b32_e32 v115, v0
	v_mov_b32_e32 v72, v0
	v_mov_b32_e32 v73, v0
	v_mov_b32_e32 v74, v0
	v_mov_b32_e32 v75, v0
	v_mov_b32_e32 v76, v0
	v_mov_b32_e32 v77, v0
	v_mov_b32_e32 v78, v0
	v_mov_b32_e32 v79, v0
	v_mov_b32_e32 v88, v0
	v_mov_b32_e32 v89, v0
	v_mov_b32_e32 v90, v0
	v_mov_b32_e32 v91, v0
	v_mov_b32_e32 v92, v0
	v_mov_b32_e32 v93, v0
	v_mov_b32_e32 v94, v0
	v_mov_b32_e32 v95, v0
	v_mov_b32_e32 v104, v0
	v_mov_b32_e32 v105, v0
	v_mov_b32_e32 v106, v0
	v_mov_b32_e32 v107, v0
	v_mov_b32_e32 v116, v0
	v_mov_b32_e32 v117, v0
	v_mov_b32_e32 v118, v0
	v_mov_b32_e32 v119, v0
	v_mov_b32_e32 v120, v0
	v_mov_b32_e32 v121, v0
	v_mov_b32_e32 v122, v0
	v_mov_b32_e32 v123, v0
	v_mov_b32_e32 v124, v0
	v_mov_b32_e32 v125, v0
	v_mov_b32_e32 v126, v0
	v_mov_b32_e32 v127, v0
	v_readlane_b32 s98, v248, 6
	v_readlane_b32 s99, v248, 7
	s_lshl_b32 s100, s67, 21
	s_lshl_b32 s101, s68, 10
	s_add_u32 s100, s100, s101
	s_nop 0
	s_add_u32 s98, s98, s100
	s_addc_u32 s99, s99, 0
	v_mov_b32_e32 v252, s98
	v_mov_b32_e32 v253, s99
	v_lshrrev_b32_e32 v254, 6, v220
	v_lshlrev_b32_e32 v254, 1, v254
	v_bfe_u32 v255, v220, 3, 1
	v_add_u32_e32 v254, v254, v255
	v_lshlrev_b32_e32 v254, 13, v254
	v_and_b32_e32 v255, 7, v220
	v_lshl_add_u32 v254, v255, 7, v254
	v_mov_b32_e32 v255, 0
	v_lshl_add_u64 v[250:251], v[254:255], 0, v[252:253]
	global_load_dword v249, v[250:251], off
.LBB0_1473:
	s_add_u32 s6, s36, 0x100
	s_addc_u32 s7, s37, 0
	s_cmp_eq_u32 s72, 28
	s_cselect_b32 s41, s23, s7
	s_cselect_b32 s40, s22, s6
	s_cselect_b32 s39, s19, s71
	s_cselect_b32 s38, s69, s70
	s_add_i32 s73, 0, 0x14000
	v_add_u32_e32 v172, s73, v181
	ds_read_b128 v[128:131], v183
	ds_read_b128 v[132:135], v183 offset:1024
	ds_read_b128 v[136:139], v183 offset:2048
	ds_read_b128 v[140:143], v183 offset:3072
	ds_read_b128 v[144:147], v172
	ds_read_b128 v[164:167], v172 offset:1024
	ds_read_b128 v[168:171], v172 offset:2048
	ds_read_b128 v[172:175], v172 offset:3072
	s_add_i32 m0, s57, 0xc000
	ds_read_b128 v[176:179], v184
	ds_read_b128 v[186:189], v184 offset:1024
	ds_read_b128 v[190:193], v184 offset:2048
	ds_read_b128 v[194:197], v184 offset:3072
	ds_read_b128 v[198:201], v184 offset:4096
	ds_read_b128 v[202:205], v184 offset:5120
	ds_read_b128 v[206:209], v184 offset:6144
	ds_read_b128 v[210:213], v184 offset:7168
	global_load_lds_dwordx4 v158, s[36:37]
	s_add_i32 m0, s57, 0xe000
	s_nop 0
	global_load_lds_dwordx4 v156, s[36:37]
	s_waitcnt vmcnt(9)
	s_waitcnt lgkmcnt(0)
	s_barrier
	s_setprio 1
	s_waitcnt lgkmcnt(0)
	v_mfma_f32_16x16x32_bf16 v[124:127], v[128:131], v[176:179], v[124:127]
	v_mfma_f32_16x16x32_bf16 v[120:123], v[136:139], v[176:179], v[120:123]
	v_mfma_f32_16x16x32_bf16 v[116:119], v[128:131], v[190:193], v[116:119]
	v_mfma_f32_16x16x32_bf16 v[104:107], v[136:139], v[190:193], v[104:107]
	v_mfma_f32_16x16x32_bf16 v[92:95], v[128:131], v[198:201], v[92:95]
	v_mfma_f32_16x16x32_bf16 v[88:91], v[136:139], v[198:201], v[88:91]
	v_mfma_f32_16x16x32_bf16 v[76:79], v[128:131], v[206:209], v[76:79]
	v_mfma_f32_16x16x32_bf16 v[72:75], v[136:139], v[206:209], v[72:75]
	v_mfma_f32_16x16x32_bf16 v[124:127], v[132:135], v[186:189], v[124:127]
	v_mfma_f32_16x16x32_bf16 v[120:123], v[140:143], v[186:189], v[120:123]
	v_mfma_f32_16x16x32_bf16 v[116:119], v[132:135], v[194:197], v[116:119]
	v_mfma_f32_16x16x32_bf16 v[104:107], v[140:143], v[194:197], v[104:107]
	v_mfma_f32_16x16x32_bf16 v[92:95], v[132:135], v[202:205], v[92:95]
	v_mfma_f32_16x16x32_bf16 v[88:91], v[140:143], v[202:205], v[88:91]
	v_mfma_f32_16x16x32_bf16 v[76:79], v[132:135], v[210:213], v[76:79]
	v_mfma_f32_16x16x32_bf16 v[72:75], v[140:143], v[210:213], v[72:75]
	s_setprio 0
	s_setprio 1
	v_mfma_f32_16x16x32_bf16 v[112:115], v[144:147], v[176:179], v[112:115]
	v_mfma_f32_16x16x32_bf16 v[108:111], v[168:171], v[176:179], v[108:111]
	v_mfma_f32_16x16x32_bf16 v[100:103], v[144:147], v[190:193], v[100:103]
	v_mfma_f32_16x16x32_bf16 v[96:99], v[168:171], v[190:193], v[96:99]
	v_mfma_f32_16x16x32_bf16 v[84:87], v[144:147], v[198:201], v[84:87]
	v_mfma_f32_16x16x32_bf16 v[80:83], v[168:171], v[198:201], v[80:83]
	v_mfma_f32_16x16x32_bf16 v[68:71], v[144:147], v[206:209], v[68:71]
	v_mfma_f32_16x16x32_bf16 v[64:67], v[168:171], v[206:209], v[64:67]
	v_mfma_f32_16x16x32_bf16 v[112:115], v[164:167], v[186:189], v[112:115]
	v_mfma_f32_16x16x32_bf16 v[108:111], v[172:175], v[186:189], v[108:111]
	v_mfma_f32_16x16x32_bf16 v[100:103], v[164:167], v[194:197], v[100:103]
	v_mfma_f32_16x16x32_bf16 v[96:99], v[172:175], v[194:197], v[96:99]
	v_mfma_f32_16x16x32_bf16 v[84:87], v[164:167], v[202:205], v[84:87]
	v_mfma_f32_16x16x32_bf16 v[80:83], v[172:175], v[202:205], v[80:83]
	v_mfma_f32_16x16x32_bf16 v[68:71], v[164:167], v[210:213], v[68:71]
	v_mfma_f32_16x16x32_bf16 v[64:67], v[172:175], v[210:213], v[64:67]
	s_setprio 0
	s_barrier
	s_add_i32 s36, s65, s56
	s_mov_b64 s[98:99], s[38:39]
	s_mov_b32 m0, s36
	ds_read_b128 v[176:179], v184 offset:16384
	ds_read_b128 v[186:189], v184 offset:17408
	ds_read_b128 v[190:193], v184 offset:18432
	ds_read_b128 v[194:197], v184 offset:19456
	ds_read_b128 v[198:201], v184 offset:20480
	ds_read_b128 v[202:205], v184 offset:21504
	ds_read_b128 v[206:209], v184 offset:22528
	ds_read_b128 v[210:213], v184 offset:23552
	global_load_lds_dwordx4 v150, s[38:39]
	s_add_i32 m0, s36, 0x2000
	s_add_u32 s36, s38, 0x80000
	s_addc_u32 s37, s39, 0
	s_add_i32 s73, s73, s56
	global_load_lds_dwordx4 v154, s[38:39]
	s_mov_b32 m0, s73
	s_mov_b64 s[100:101], s[40:41]
	global_load_lds_dwordx4 v150, s[36:37]
	s_add_i32 m0, s73, 0x2000
	s_nop 0
	global_load_lds_dwordx4 v154, s[36:37]
	s_mov_b32 m0, s57
	s_nop 0
	global_load_lds_dwordx4 v148, s[40:41]
	s_mov_b32 m0, s58
	s_nop 0
	global_load_lds_dwordx4 v152, s[40:41]
	s_waitcnt vmcnt(9)
	s_waitcnt lgkmcnt(0)
	s_barrier
	s_setprio 1
	s_waitcnt lgkmcnt(0)
	v_mfma_f32_16x16x32_bf16 v[60:63], v[128:131], v[176:179], v[60:63]
	v_mfma_f32_16x16x32_bf16 v[56:59], v[136:139], v[176:179], v[56:59]
	v_mfma_f32_16x16x32_bf16 v[52:55], v[128:131], v[190:193], v[52:55]
	v_mfma_f32_16x16x32_bf16 v[40:43], v[136:139], v[190:193], v[40:43]
	v_mfma_f32_16x16x32_bf16 v[28:31], v[128:131], v[198:201], v[28:31]
	v_mfma_f32_16x16x32_bf16 v[24:27], v[136:139], v[198:201], v[24:27]
	v_mfma_f32_16x16x32_bf16 v[12:15], v[128:131], v[206:209], v[12:15]
	v_mfma_f32_16x16x32_bf16 v[8:11], v[136:139], v[206:209], v[8:11]
	v_mfma_f32_16x16x32_bf16 v[60:63], v[132:135], v[186:189], v[60:63]
	v_mfma_f32_16x16x32_bf16 v[56:59], v[140:143], v[186:189], v[56:59]
	v_mfma_f32_16x16x32_bf16 v[52:55], v[132:135], v[194:197], v[52:55]
	v_mfma_f32_16x16x32_bf16 v[40:43], v[140:143], v[194:197], v[40:43]
	v_mfma_f32_16x16x32_bf16 v[28:31], v[132:135], v[202:205], v[28:31]
	v_mfma_f32_16x16x32_bf16 v[24:27], v[140:143], v[202:205], v[24:27]
	v_mfma_f32_16x16x32_bf16 v[12:15], v[132:135], v[210:213], v[12:15]
	v_mfma_f32_16x16x32_bf16 v[8:11], v[140:143], v[210:213], v[8:11]
	s_setprio 0
	s_setprio 1
	v_mfma_f32_16x16x32_bf16 v[48:51], v[144:147], v[176:179], v[48:51]
	v_mfma_f32_16x16x32_bf16 v[44:47], v[168:171], v[176:179], v[44:47]
	v_mfma_f32_16x16x32_bf16 v[36:39], v[144:147], v[190:193], v[36:39]
	v_mfma_f32_16x16x32_bf16 v[32:35], v[168:171], v[190:193], v[32:35]
	v_mfma_f32_16x16x32_bf16 v[20:23], v[144:147], v[198:201], v[20:23]
	v_mfma_f32_16x16x32_bf16 v[16:19], v[168:171], v[198:201], v[16:19]
	v_mfma_f32_16x16x32_bf16 v[4:7], v[144:147], v[206:209], v[4:7]
	v_mfma_f32_16x16x32_bf16 v[0:3], v[168:171], v[206:209], v[0:3]
	v_mfma_f32_16x16x32_bf16 v[48:51], v[164:167], v[186:189], v[48:51]
	v_mfma_f32_16x16x32_bf16 v[44:47], v[172:175], v[186:189], v[44:47]
	v_mfma_f32_16x16x32_bf16 v[36:39], v[164:167], v[194:197], v[36:39]
	v_mfma_f32_16x16x32_bf16 v[32:35], v[172:175], v[194:197], v[32:35]
	v_mfma_f32_16x16x32_bf16 v[20:23], v[164:167], v[202:205], v[20:23]
	v_mfma_f32_16x16x32_bf16 v[16:19], v[172:175], v[202:205], v[16:19]
	v_mfma_f32_16x16x32_bf16 v[4:7], v[164:167], v[210:213], v[4:7]
	v_mfma_f32_16x16x32_bf16 v[0:3], v[172:175], v[210:213], v[0:3]
	s_setprio 0
	s_barrier
	s_add_i32 s73, 0, 0x18000
	s_add_i32 s74, 0, 0x1c000
	v_add_u32_e32 v140, s73, v181
	v_add_u32_e32 v172, s74, v181
	ds_read_b128 v[128:131], v140
	ds_read_b128 v[132:135], v140 offset:1024
	ds_read_b128 v[136:139], v140 offset:2048
	ds_read_b128 v[140:143], v140 offset:3072
	ds_read_b128 v[144:147], v172
	ds_read_b128 v[164:167], v172 offset:1024
	ds_read_b128 v[168:171], v172 offset:2048
	ds_read_b128 v[172:175], v172 offset:3072
	s_add_u32 s36, s40, 0x140000
	s_addc_u32 s37, s41, 0
	s_mov_b32 m0, s59
	ds_read_b128 v[176:179], v184 offset:32768
	ds_read_b128 v[186:189], v184 offset:33792
	ds_read_b128 v[190:193], v184 offset:34816
	ds_read_b128 v[194:197], v184 offset:35840
	ds_read_b128 v[198:201], v184 offset:36864
	ds_read_b128 v[202:205], v184 offset:37888
	ds_read_b128 v[206:209], v184 offset:38912
	ds_read_b128 v[210:213], v184 offset:39936
	global_load_lds_dwordx4 v148, s[36:37]
	s_mov_b32 m0, s60
	s_nop 0
	global_load_lds_dwordx4 v152, s[36:37]
	s_waitcnt vmcnt(8)
	s_waitcnt lgkmcnt(0)
	s_barrier
	s_setprio 1
	s_waitcnt lgkmcnt(0)
	v_mfma_f32_16x16x32_bf16 v[124:127], v[128:131], v[176:179], v[124:127]
	v_mfma_f32_16x16x32_bf16 v[120:123], v[136:139], v[176:179], v[120:123]
	v_mfma_f32_16x16x32_bf16 v[116:119], v[128:131], v[190:193], v[116:119]
	v_mfma_f32_16x16x32_bf16 v[104:107], v[136:139], v[190:193], v[104:107]
	v_mfma_f32_16x16x32_bf16 v[92:95], v[128:131], v[198:201], v[92:95]
	v_mfma_f32_16x16x32_bf16 v[88:91], v[136:139], v[198:201], v[88:91]
	v_mfma_f32_16x16x32_bf16 v[76:79], v[128:131], v[206:209], v[76:79]
	v_mfma_f32_16x16x32_bf16 v[72:75], v[136:139], v[206:209], v[72:75]
	v_mfma_f32_16x16x32_bf16 v[124:127], v[132:135], v[186:189], v[124:127]
	v_mfma_f32_16x16x32_bf16 v[120:123], v[140:143], v[186:189], v[120:123]
	v_mfma_f32_16x16x32_bf16 v[116:119], v[132:135], v[194:197], v[116:119]
	v_mfma_f32_16x16x32_bf16 v[104:107], v[140:143], v[194:197], v[104:107]
	v_mfma_f32_16x16x32_bf16 v[92:95], v[132:135], v[202:205], v[92:95]
	v_mfma_f32_16x16x32_bf16 v[88:91], v[140:143], v[202:205], v[88:91]
	v_mfma_f32_16x16x32_bf16 v[76:79], v[132:135], v[210:213], v[76:79]
	v_mfma_f32_16x16x32_bf16 v[72:75], v[140:143], v[210:213], v[72:75]
	s_setprio 0
	s_setprio 1
	v_mfma_f32_16x16x32_bf16 v[112:115], v[144:147], v[176:179], v[112:115]
	v_mfma_f32_16x16x32_bf16 v[108:111], v[168:171], v[176:179], v[108:111]
	v_mfma_f32_16x16x32_bf16 v[100:103], v[144:147], v[190:193], v[100:103]
	v_mfma_f32_16x16x32_bf16 v[96:99], v[168:171], v[190:193], v[96:99]
	v_mfma_f32_16x16x32_bf16 v[84:87], v[144:147], v[198:201], v[84:87]
	v_mfma_f32_16x16x32_bf16 v[80:83], v[168:171], v[198:201], v[80:83]
	v_mfma_f32_16x16x32_bf16 v[68:71], v[144:147], v[206:209], v[68:71]
	v_mfma_f32_16x16x32_bf16 v[64:67], v[168:171], v[206:209], v[64:67]
	v_mfma_f32_16x16x32_bf16 v[112:115], v[164:167], v[186:189], v[112:115]
	v_mfma_f32_16x16x32_bf16 v[108:111], v[172:175], v[186:189], v[108:111]
	v_mfma_f32_16x16x32_bf16 v[100:103], v[164:167], v[194:197], v[100:103]
	v_mfma_f32_16x16x32_bf16 v[96:99], v[172:175], v[194:197], v[96:99]
	v_mfma_f32_16x16x32_bf16 v[84:87], v[164:167], v[202:205], v[84:87]
	v_mfma_f32_16x16x32_bf16 v[80:83], v[172:175], v[202:205], v[80:83]
	v_mfma_f32_16x16x32_bf16 v[68:71], v[164:167], v[210:213], v[68:71]
	v_mfma_f32_16x16x32_bf16 v[64:67], v[172:175], v[210:213], v[64:67]
	s_setprio 0
	s_barrier
	s_add_i32 s36, s73, s56
	s_add_i32 m0, s36, 0xffffff80
	ds_read_b128 v[176:179], v184 offset:49152
	ds_read_b128 v[186:189], v184 offset:50176
	ds_read_b128 v[190:193], v184 offset:51200
	ds_read_b128 v[194:197], v184 offset:52224
	ds_read_b128 v[198:201], v184 offset:53248
	ds_read_b128 v[202:205], v184 offset:54272
	ds_read_b128 v[206:209], v184 offset:55296
	ds_read_b128 v[210:213], v184 offset:56320
	global_load_lds_dwordx4 v150, s[98:99] offset:128
	s_add_i32 m0, s36, 0x1f80
	s_add_u32 s36, s38, 0x80080
	s_addc_u32 s37, s39, 0
	s_add_i32 s38, s74, s56
	global_load_lds_dwordx4 v154, s[98:99] offset:128
	s_mov_b32 m0, s38
	s_nop 0
	global_load_lds_dwordx4 v150, s[36:37]
	s_add_i32 m0, s38, 0x2000
	s_nop 0
	global_load_lds_dwordx4 v154, s[36:37]
	s_add_i32 m0, s62, 0xffffff80
	s_nop 0
	global_load_lds_dwordx4 v148, s[100:101] offset:128
	s_add_i32 m0, s63, 0xffffff80
	s_nop 0
	global_load_lds_dwordx4 v152, s[100:101] offset:128
	v_add_u32_e32 v254, 0x20000, v254
	v_and_b32_e32 v254, 0x1fffff, v254
	v_lshl_add_u64 v[250:251], v[254:255], 0, v[252:253]
	global_load_dword v249, v[250:251], off
	s_waitcnt vmcnt(9)
	s_waitcnt lgkmcnt(0)
	s_barrier
	s_setprio 1
	s_waitcnt lgkmcnt(0)
	v_mfma_f32_16x16x32_bf16 v[60:63], v[128:131], v[176:179], v[60:63]
	v_mfma_f32_16x16x32_bf16 v[56:59], v[136:139], v[176:179], v[56:59]
	v_mfma_f32_16x16x32_bf16 v[52:55], v[128:131], v[190:193], v[52:55]
	v_mfma_f32_16x16x32_bf16 v[40:43], v[136:139], v[190:193], v[40:43]
	v_mfma_f32_16x16x32_bf16 v[28:31], v[128:131], v[198:201], v[28:31]
	v_mfma_f32_16x16x32_bf16 v[24:27], v[136:139], v[198:201], v[24:27]
	v_mfma_f32_16x16x32_bf16 v[12:15], v[128:131], v[206:209], v[12:15]
	v_mfma_f32_16x16x32_bf16 v[8:11], v[136:139], v[206:209], v[8:11]
	v_mfma_f32_16x16x32_bf16 v[60:63], v[132:135], v[186:189], v[60:63]
	v_mfma_f32_16x16x32_bf16 v[56:59], v[140:143], v[186:189], v[56:59]
	v_mfma_f32_16x16x32_bf16 v[52:55], v[132:135], v[194:197], v[52:55]
	v_mfma_f32_16x16x32_bf16 v[40:43], v[140:143], v[194:197], v[40:43]
	v_mfma_f32_16x16x32_bf16 v[28:31], v[132:135], v[202:205], v[28:31]
	v_mfma_f32_16x16x32_bf16 v[24:27], v[140:143], v[202:205], v[24:27]
	v_mfma_f32_16x16x32_bf16 v[12:15], v[132:135], v[210:213], v[12:15]
	v_mfma_f32_16x16x32_bf16 v[8:11], v[140:143], v[210:213], v[8:11]
	s_setprio 0
	s_setprio 1
	v_mfma_f32_16x16x32_bf16 v[48:51], v[144:147], v[176:179], v[48:51]
	v_mfma_f32_16x16x32_bf16 v[44:47], v[168:171], v[176:179], v[44:47]
	v_mfma_f32_16x16x32_bf16 v[36:39], v[144:147], v[190:193], v[36:39]
	v_mfma_f32_16x16x32_bf16 v[32:35], v[168:171], v[190:193], v[32:35]
	v_mfma_f32_16x16x32_bf16 v[20:23], v[144:147], v[198:201], v[20:23]
	v_mfma_f32_16x16x32_bf16 v[16:19], v[168:171], v[198:201], v[16:19]
	v_mfma_f32_16x16x32_bf16 v[4:7], v[144:147], v[206:209], v[4:7]
	v_mfma_f32_16x16x32_bf16 v[0:3], v[168:171], v[206:209], v[0:3]
	v_mfma_f32_16x16x32_bf16 v[48:51], v[164:167], v[186:189], v[48:51]
	v_mfma_f32_16x16x32_bf16 v[44:47], v[172:175], v[186:189], v[44:47]
	v_mfma_f32_16x16x32_bf16 v[36:39], v[164:167], v[194:197], v[36:39]
	v_mfma_f32_16x16x32_bf16 v[32:35], v[172:175], v[194:197], v[32:35]
	v_mfma_f32_16x16x32_bf16 v[20:23], v[164:167], v[202:205], v[20:23]
	v_mfma_f32_16x16x32_bf16 v[16:19], v[172:175], v[202:205], v[16:19]
	v_mfma_f32_16x16x32_bf16 v[4:7], v[164:167], v[210:213], v[4:7]
	v_mfma_f32_16x16x32_bf16 v[0:3], v[172:175], v[210:213], v[0:3]
	s_setprio 0
	s_barrier
	s_add_i32 s72, s72, 2
	s_add_u32 s70, s70, 0x100
	s_addc_u32 s71, s71, 0
	s_cmp_gt_u32 s72, 29
	s_mov_b64 s[36:37], s[6:7]
	s_cbranch_scc0 .LBB0_1473
	s_and_b64 vcc, exec, s[16:17]
	s_cbranch_vccz .LBB0_1476
	s_barrier

.LBB0_1945:
	s_ashr_i32 s21, s20, 31
	s_lshl_b64 s[22:23], s[20:21], 22
	s_add_u32 s22, s46, s22
	s_addc_u32 s23, s47, s23
	s_and_b64 s[34:35], s[2:3], exec
	s_cselect_b32 s21, s23, s39
	s_cselect_b32 s61, s22, s38
	s_ashr_i32 s19, s18, 31
	s_lshl_b64 s[34:35], s[18:19], 20
	s_add_u32 s34, s48, s34
	s_addc_u32 s35, s49, s35
	s_and_b64 s[42:43], s[2:3], exec
	s_cselect_b32 s19, s35, s41
	s_cselect_b32 s62, s34, s40
	s_add_u32 s38, s38, 0x200080
	s_addc_u32 s39, s39, 0
	s_add_u32 s63, s40, 0x100
	v_mov_b32_e32 v0, 0
	s_addc_u32 s64, s41, 0
	s_mov_b32 s65, -2
	v_mov_b32_e32 v1, v0
	v_mov_b32_e32 v2, v0
	v_mov_b32_e32 v3, v0
	v_mov_b32_e32 v4, v0
	v_mov_b32_e32 v5, v0
	v_mov_b32_e32 v6, v0
	v_mov_b32_e32 v7, v0
	v_mov_b32_e32 v12, v0
	v_mov_b32_e32 v13, v0
	v_mov_b32_e32 v14, v0
	v_mov_b32_e32 v15, v0
	v_mov_b32_e32 v16, v0
	v_mov_b32_e32 v17, v0
	v_mov_b32_e32 v18, v0
	v_mov_b32_e32 v19, v0
	s_waitcnt vmcnt(0)
	v_mov_b32_e32 v24, v0
	v_mov_b32_e32 v25, v0
	v_mov_b32_e32 v26, v0
	v_mov_b32_e32 v27, v0
	v_mov_b32_e32 v32, v0
	v_mov_b32_e32 v33, v0
	v_mov_b32_e32 v34, v0
	v_mov_b32_e32 v35, v0
	v_mov_b32_e32 v40, v0
	v_mov_b32_e32 v41, v0
	v_mov_b32_e32 v42, v0
	v_mov_b32_e32 v43, v0
	v_mov_b32_e32 v48, v0
	v_mov_b32_e32 v49, v0
	v_mov_b32_e32 v50, v0
	v_mov_b32_e32 v51, v0
	v_mov_b32_e32 v8, v0
	v_mov_b32_e32 v9, v0
	v_mov_b32_e32 v10, v0
	v_mov_b32_e32 v11, v0
	v_mov_b32_e32 v20, v0
	v_mov_b32_e32 v21, v0
	v_mov_b32_e32 v22, v0
	v_mov_b32_e32 v23, v0
	v_mov_b32_e32 v28, v0
	v_mov_b32_e32 v29, v0
	v_mov_b32_e32 v30, v0
	v_mov_b32_e32 v31, v0
	v_mov_b32_e32 v36, v0
	v_mov_b32_e32 v37, v0
	v_mov_b32_e32 v38, v0
	v_mov_b32_e32 v39, v0
	v_mov_b32_e32 v44, v0
	v_mov_b32_e32 v45, v0
	v_mov_b32_e32 v46, v0
	v_mov_b32_e32 v47, v0
	v_mov_b32_e32 v52, v0
	v_mov_b32_e32 v53, v0
	v_mov_b32_e32 v54, v0
	v_mov_b32_e32 v55, v0
	v_mov_b32_e32 v56, v0
	v_mov_b32_e32 v57, v0
	v_mov_b32_e32 v58, v0
	v_mov_b32_e32 v59, v0
	v_mov_b32_e32 v60, v0
	v_mov_b32_e32 v61, v0
	v_mov_b32_e32 v62, v0
	v_mov_b32_e32 v63, v0
	v_mov_b32_e32 v64, v0
	v_mov_b32_e32 v65, v0
	v_mov_b32_e32 v66, v0
	v_mov_b32_e32 v67, v0
	v_mov_b32_e32 v68, v0
	v_mov_b32_e32 v69, v0
	v_mov_b32_e32 v70, v0
	v_mov_b32_e32 v71, v0
	v_mov_b32_e32 v72, v0
	v_mov_b32_e32 v73, v0
	v_mov_b32_e32 v74, v0
	v_mov_b32_e32 v75, v0
	v_mov_b32_e32 v76, v0
	v_mov_b32_e32 v77, v0
	v_mov_b32_e32 v78, v0
	v_mov_b32_e32 v79, v0
	v_mov_b32_e32 v84, v0
	v_mov_b32_e32 v85, v0
	v_mov_b32_e32 v86, v0
	v_mov_b32_e32 v87, v0
	v_mov_b32_e32 v92, v0
	v_mov_b32_e32 v93, v0
	v_mov_b32_e32 v94, v0
	v_mov_b32_e32 v95, v0
	v_mov_b32_e32 v100, v0
	v_mov_b32_e32 v101, v0
	v_mov_b32_e32 v102, v0
	v_mov_b32_e32 v103, v0
	v_mov_b32_e32 v108, v0
	v_mov_b32_e32 v109, v0
	v_mov_b32_e32 v110, v0
	v_mov_b32_e32 v111, v0
	v_mov_b32_e32 v80, v0
	v_mov_b32_e32 v81, v0
	v_mov_b32_e32 v82, v0
	v_mov_b32_e32 v83, v0
	v_mov_b32_e32 v88, v0
	v_mov_b32_e32 v89, v0
	v_mov_b32_e32 v90, v0
	v_mov_b32_e32 v91, v0
	v_mov_b32_e32 v96, v0
	v_mov_b32_e32 v97, v0
	v_mov_b32_e32 v98, v0
	v_mov_b32_e32 v99, v0
	v_mov_b32_e32 v104, v0
	v_mov_b32_e32 v105, v0
	v_mov_b32_e32 v106, v0
	v_mov_b32_e32 v107, v0
	v_mov_b32_e32 v112, v0
	v_mov_b32_e32 v113, v0
	v_mov_b32_e32 v114, v0
	v_mov_b32_e32 v115, v0
	v_mov_b32_e32 v116, v0
	v_mov_b32_e32 v117, v0
	v_mov_b32_e32 v118, v0
	v_mov_b32_e32 v119, v0
	v_mov_b32_e32 v120, v0
	v_mov_b32_e32 v121, v0
	v_mov_b32_e32 v122, v0
	v_mov_b32_e32 v123, v0
	v_mov_b32_e32 v124, v0
	v_mov_b32_e32 v125, v0
	v_mov_b32_e32 v126, v0
	v_mov_b32_e32 v127, v0
	v_readlane_b32 s98, v248, 6
	v_readlane_b32 s99, v248, 7
	s_lshl_b32 s100, s36, 21
	s_lshl_b32 s101, s37, 10
	s_add_u32 s100, s100, s101
	s_nop 0
	s_add_u32 s98, s98, s100
	s_addc_u32 s99, s99, 0
	v_mov_b32_e32 v252, s98
	v_mov_b32_e32 v253, s99
	v_lshrrev_b32_e32 v254, 6, v220
	v_lshlrev_b32_e32 v254, 1, v254
	v_bfe_u32 v255, v220, 3, 1
	v_add_u32_e32 v254, v254, v255
	v_lshlrev_b32_e32 v254, 13, v254
	v_and_b32_e32 v255, 7, v220
	v_lshl_add_u32 v254, v255, 7, v254
	v_mov_b32_e32 v255, 0
	v_lshl_add_u64 v[250:251], v[254:255], 0, v[252:253]
	global_load_dword v249, v[250:251], off
.LBB0_1946:
	ds_read_b128 v[144:147], v159
	ds_read_b128 v[148:151], v159 offset:1024
	ds_read_b128 v[152:155], v159 offset:2048
	ds_read_b128 v[162:165], v159 offset:3072
	ds_read_b128 v[166:169], v160
	ds_read_b128 v[170:173], v160 offset:1024
	ds_read_b128 v[174:177], v160 offset:2048
	ds_read_b128 v[178:181], v160 offset:3072
	s_add_u32 s40, s38, 0xffe00080
	s_addc_u32 s41, s39, -1
	s_cmp_eq_u32 s65, 28
	s_cselect_b32 s43, s21, s41
	s_cselect_b32 s42, s61, s40
	s_cselect_b32 s41, s19, s64
	s_cselect_b32 s40, s62, s63
	s_add_i32 m0, s51, 0xc000
	ds_read_b128 v[182:185], v161
	ds_read_b128 v[186:189], v161 offset:1024
	ds_read_b128 v[190:193], v161 offset:2048
	ds_read_b128 v[194:197], v161 offset:3072
	ds_read_b128 v[198:201], v161 offset:4096
	ds_read_b128 v[202:205], v161 offset:5120
	ds_read_b128 v[206:209], v161 offset:6144
	ds_read_b128 v[210:213], v161 offset:7168
	global_load_lds_dwordx4 v136, s[38:39]
	s_add_i32 m0, s51, 0xe000
	s_nop 0
	global_load_lds_dwordx4 v138, s[38:39]
	s_waitcnt vmcnt(9)
	s_waitcnt lgkmcnt(0)
	s_barrier
	s_setprio 1
	s_waitcnt lgkmcnt(0)
	v_mfma_f32_16x16x32_bf16 v[124:127], v[144:147], v[182:185], v[124:127]
	v_mfma_f32_16x16x32_bf16 v[120:123], v[152:155], v[182:185], v[120:123]
	v_mfma_f32_16x16x32_bf16 v[116:119], v[144:147], v[190:193], v[116:119]
	v_mfma_f32_16x16x32_bf16 v[112:115], v[152:155], v[190:193], v[112:115]
	v_mfma_f32_16x16x32_bf16 v[104:107], v[144:147], v[198:201], v[104:107]
	v_mfma_f32_16x16x32_bf16 v[96:99], v[152:155], v[198:201], v[96:99]
	v_mfma_f32_16x16x32_bf16 v[88:91], v[144:147], v[206:209], v[88:91]
	v_mfma_f32_16x16x32_bf16 v[80:83], v[152:155], v[206:209], v[80:83]
	v_mfma_f32_16x16x32_bf16 v[124:127], v[148:151], v[186:189], v[124:127]
	v_mfma_f32_16x16x32_bf16 v[120:123], v[162:165], v[186:189], v[120:123]
	v_mfma_f32_16x16x32_bf16 v[116:119], v[148:151], v[194:197], v[116:119]
	v_mfma_f32_16x16x32_bf16 v[112:115], v[162:165], v[194:197], v[112:115]
	v_mfma_f32_16x16x32_bf16 v[104:107], v[148:151], v[202:205], v[104:107]
	v_mfma_f32_16x16x32_bf16 v[96:99], v[162:165], v[202:205], v[96:99]
	v_mfma_f32_16x16x32_bf16 v[88:91], v[148:151], v[210:213], v[88:91]
	v_mfma_f32_16x16x32_bf16 v[80:83], v[162:165], v[210:213], v[80:83]
	s_setprio 0
	s_setprio 1
	v_mfma_f32_16x16x32_bf16 v[108:111], v[166:169], v[182:185], v[108:111]
	v_mfma_f32_16x16x32_bf16 v[100:103], v[174:177], v[182:185], v[100:103]
	v_mfma_f32_16x16x32_bf16 v[92:95], v[166:169], v[190:193], v[92:95]
	v_mfma_f32_16x16x32_bf16 v[84:87], v[174:177], v[190:193], v[84:87]
	v_mfma_f32_16x16x32_bf16 v[76:79], v[166:169], v[198:201], v[76:79]
	v_mfma_f32_16x16x32_bf16 v[72:75], v[174:177], v[198:201], v[72:75]
	v_mfma_f32_16x16x32_bf16 v[68:71], v[166:169], v[206:209], v[68:71]
	v_mfma_f32_16x16x32_bf16 v[64:67], v[174:177], v[206:209], v[64:67]
	v_mfma_f32_16x16x32_bf16 v[108:111], v[170:173], v[186:189], v[108:111]
	v_mfma_f32_16x16x32_bf16 v[100:103], v[178:181], v[186:189], v[100:103]
	v_mfma_f32_16x16x32_bf16 v[92:95], v[170:173], v[194:197], v[92:95]
	v_mfma_f32_16x16x32_bf16 v[84:87], v[178:181], v[194:197], v[84:87]
	v_mfma_f32_16x16x32_bf16 v[76:79], v[170:173], v[202:205], v[76:79]
	v_mfma_f32_16x16x32_bf16 v[72:75], v[178:181], v[202:205], v[72:75]
	v_mfma_f32_16x16x32_bf16 v[68:71], v[170:173], v[210:213], v[68:71]
	v_mfma_f32_16x16x32_bf16 v[64:67], v[178:181], v[210:213], v[64:67]
	s_setprio 0
	s_barrier
	s_add_i32 s66, s59, s50
	s_mov_b64 s[98:99], s[40:41]
	s_mov_b32 m0, s66
	ds_read_b128 v[182:185], v161 offset:16384
	ds_read_b128 v[186:189], v161 offset:17408
	ds_read_b128 v[190:193], v161 offset:18432
	ds_read_b128 v[194:197], v161 offset:19456
	ds_read_b128 v[198:201], v161 offset:20480
	ds_read_b128 v[202:205], v161 offset:21504
	ds_read_b128 v[206:209], v161 offset:22528
	ds_read_b128 v[210:213], v161 offset:23552
	global_load_lds_dwordx4 v130, s[40:41]
	s_add_i32 m0, s66, 0x2000
	s_add_u32 s66, s40, 0x80000
	s_addc_u32 s67, s41, 0
	s_add_i32 s68, s60, s50
	global_load_lds_dwordx4 v134, s[40:41]
	s_mov_b32 m0, s68
	s_mov_b64 s[100:101], s[42:43]
	global_load_lds_dwordx4 v130, s[66:67]
	s_add_i32 m0, s68, 0x2000
	s_nop 0
	global_load_lds_dwordx4 v134, s[66:67]
	s_mov_b32 m0, s51
	s_nop 0
	global_load_lds_dwordx4 v128, s[42:43]
	s_mov_b32 m0, s52
	s_nop 0
	global_load_lds_dwordx4 v132, s[42:43]
	s_waitcnt vmcnt(9)
	s_waitcnt lgkmcnt(0)
	s_barrier
	s_setprio 1
	s_waitcnt lgkmcnt(0)
	v_mfma_f32_16x16x32_bf16 v[60:63], v[144:147], v[182:185], v[60:63]
	v_mfma_f32_16x16x32_bf16 v[56:59], v[152:155], v[182:185], v[56:59]
	v_mfma_f32_16x16x32_bf16 v[52:55], v[144:147], v[190:193], v[52:55]
	v_mfma_f32_16x16x32_bf16 v[44:47], v[152:155], v[190:193], v[44:47]
	v_mfma_f32_16x16x32_bf16 v[36:39], v[144:147], v[198:201], v[36:39]
	v_mfma_f32_16x16x32_bf16 v[28:31], v[152:155], v[198:201], v[28:31]
	v_mfma_f32_16x16x32_bf16 v[20:23], v[144:147], v[206:209], v[20:23]
	v_mfma_f32_16x16x32_bf16 v[8:11], v[152:155], v[206:209], v[8:11]
	v_mfma_f32_16x16x32_bf16 v[60:63], v[148:151], v[186:189], v[60:63]
	v_mfma_f32_16x16x32_bf16 v[56:59], v[162:165], v[186:189], v[56:59]
	v_mfma_f32_16x16x32_bf16 v[52:55], v[148:151], v[194:197], v[52:55]
	v_mfma_f32_16x16x32_bf16 v[44:47], v[162:165], v[194:197], v[44:47]
	v_mfma_f32_16x16x32_bf16 v[36:39], v[148:151], v[202:205], v[36:39]
	v_mfma_f32_16x16x32_bf16 v[28:31], v[162:165], v[202:205], v[28:31]
	v_mfma_f32_16x16x32_bf16 v[20:23], v[148:151], v[210:213], v[20:23]
	v_mfma_f32_16x16x32_bf16 v[8:11], v[162:165], v[210:213], v[8:11]
	s_setprio 0
	s_setprio 1
	v_mfma_f32_16x16x32_bf16 v[48:51], v[166:169], v[182:185], v[48:51]
	v_mfma_f32_16x16x32_bf16 v[40:43], v[174:177], v[182:185], v[40:43]
	v_mfma_f32_16x16x32_bf16 v[32:35], v[166:169], v[190:193], v[32:35]
	v_mfma_f32_16x16x32_bf16 v[24:27], v[174:177], v[190:193], v[24:27]
	v_mfma_f32_16x16x32_bf16 v[16:19], v[166:169], v[198:201], v[16:19]
	v_mfma_f32_16x16x32_bf16 v[12:15], v[174:177], v[198:201], v[12:15]
	v_mfma_f32_16x16x32_bf16 v[4:7], v[166:169], v[206:209], v[4:7]
	v_mfma_f32_16x16x32_bf16 v[0:3], v[174:177], v[206:209], v[0:3]
	v_mfma_f32_16x16x32_bf16 v[48:51], v[170:173], v[186:189], v[48:51]
	v_mfma_f32_16x16x32_bf16 v[40:43], v[178:181], v[186:189], v[40:43]
	v_mfma_f32_16x16x32_bf16 v[32:35], v[170:173], v[194:197], v[32:35]
	v_mfma_f32_16x16x32_bf16 v[24:27], v[178:181], v[194:197], v[24:27]
	v_mfma_f32_16x16x32_bf16 v[16:19], v[170:173], v[202:205], v[16:19]
	v_mfma_f32_16x16x32_bf16 v[12:15], v[178:181], v[202:205], v[12:15]
	v_mfma_f32_16x16x32_bf16 v[4:7], v[170:173], v[210:213], v[4:7]
	v_mfma_f32_16x16x32_bf16 v[0:3], v[178:181], v[210:213], v[0:3]
	s_setprio 0
	s_barrier
	s_add_i32 s66, 0, 0x18000
	s_add_i32 s67, 0, 0x1c000
	v_add_u32_e32 v162, s66, v157
	v_add_u32_e32 v178, s67, v157
	ds_read_b128 v[144:147], v162
	ds_read_b128 v[148:151], v162 offset:1024
	ds_read_b128 v[152:155], v162 offset:2048
	ds_read_b128 v[162:165], v162 offset:3072
	ds_read_b128 v[166:169], v178
	ds_read_b128 v[170:173], v178 offset:1024
	ds_read_b128 v[174:177], v178 offset:2048
	ds_read_b128 v[178:181], v178 offset:3072
	s_add_u32 s42, s42, 0x200000
	s_addc_u32 s43, s43, 0
	s_mov_b32 m0, s53
	ds_read_b128 v[182:185], v161 offset:32768
	ds_read_b128 v[186:189], v161 offset:33792
	ds_read_b128 v[190:193], v161 offset:34816
	ds_read_b128 v[194:197], v161 offset:35840
	ds_read_b128 v[198:201], v161 offset:36864
	ds_read_b128 v[202:205], v161 offset:37888
	ds_read_b128 v[206:209], v161 offset:38912
	ds_read_b128 v[210:213], v161 offset:39936
	global_load_lds_dwordx4 v128, s[42:43]
	s_mov_b32 m0, s54
	s_nop 0
	global_load_lds_dwordx4 v132, s[42:43]
	s_waitcnt vmcnt(8)
	s_waitcnt lgkmcnt(0)
	s_barrier
	s_setprio 1
	s_waitcnt lgkmcnt(0)
	v_mfma_f32_16x16x32_bf16 v[124:127], v[144:147], v[182:185], v[124:127]
	v_mfma_f32_16x16x32_bf16 v[120:123], v[152:155], v[182:185], v[120:123]
	v_mfma_f32_16x16x32_bf16 v[116:119], v[144:147], v[190:193], v[116:119]
	v_mfma_f32_16x16x32_bf16 v[112:115], v[152:155], v[190:193], v[112:115]
	v_mfma_f32_16x16x32_bf16 v[104:107], v[144:147], v[198:201], v[104:107]
	v_mfma_f32_16x16x32_bf16 v[96:99], v[152:155], v[198:201], v[96:99]
	v_mfma_f32_16x16x32_bf16 v[88:91], v[144:147], v[206:209], v[88:91]
	v_mfma_f32_16x16x32_bf16 v[80:83], v[152:155], v[206:209], v[80:83]
	v_mfma_f32_16x16x32_bf16 v[124:127], v[148:151], v[186:189], v[124:127]
	v_mfma_f32_16x16x32_bf16 v[120:123], v[162:165], v[186:189], v[120:123]
	v_mfma_f32_16x16x32_bf16 v[116:119], v[148:151], v[194:197], v[116:119]
	v_mfma_f32_16x16x32_bf16 v[112:115], v[162:165], v[194:197], v[112:115]
	v_mfma_f32_16x16x32_bf16 v[104:107], v[148:151], v[202:205], v[104:107]
	v_mfma_f32_16x16x32_bf16 v[96:99], v[162:165], v[202:205], v[96:99]
	v_mfma_f32_16x16x32_bf16 v[88:91], v[148:151], v[210:213], v[88:91]
	v_mfma_f32_16x16x32_bf16 v[80:83], v[162:165], v[210:213], v[80:83]
	s_setprio 0
	s_setprio 1
	v_mfma_f32_16x16x32_bf16 v[108:111], v[166:169], v[182:185], v[108:111]
	v_mfma_f32_16x16x32_bf16 v[100:103], v[174:177], v[182:185], v[100:103]
	v_mfma_f32_16x16x32_bf16 v[92:95], v[166:169], v[190:193], v[92:95]
	v_mfma_f32_16x16x32_bf16 v[84:87], v[174:177], v[190:193], v[84:87]
	v_mfma_f32_16x16x32_bf16 v[76:79], v[166:169], v[198:201], v[76:79]
	v_mfma_f32_16x16x32_bf16 v[72:75], v[174:177], v[198:201], v[72:75]
	v_mfma_f32_16x16x32_bf16 v[68:71], v[166:169], v[206:209], v[68:71]
	v_mfma_f32_16x16x32_bf16 v[64:67], v[174:177], v[206:209], v[64:67]
	v_mfma_f32_16x16x32_bf16 v[108:111], v[170:173], v[186:189], v[108:111]
	v_mfma_f32_16x16x32_bf16 v[100:103], v[178:181], v[186:189], v[100:103]
	v_mfma_f32_16x16x32_bf16 v[92:95], v[170:173], v[194:197], v[92:95]
	v_mfma_f32_16x16x32_bf16 v[84:87], v[178:181], v[194:197], v[84:87]
	v_mfma_f32_16x16x32_bf16 v[76:79], v[170:173], v[202:205], v[76:79]
	v_mfma_f32_16x16x32_bf16 v[72:75], v[178:181], v[202:205], v[72:75]
	v_mfma_f32_16x16x32_bf16 v[68:71], v[170:173], v[210:213], v[68:71]
	v_mfma_f32_16x16x32_bf16 v[64:67], v[178:181], v[210:213], v[64:67]
	s_setprio 0
	s_barrier
	s_add_i32 s42, s66, s50
	s_add_i32 m0, s42, 0xffffff80
	ds_read_b128 v[182:185], v161 offset:49152
	ds_read_b128 v[186:189], v161 offset:50176
	ds_read_b128 v[190:193], v161 offset:51200
	ds_read_b128 v[194:197], v161 offset:52224
	ds_read_b128 v[198:201], v161 offset:53248
	ds_read_b128 v[202:205], v161 offset:54272
	ds_read_b128 v[206:209], v161 offset:55296
	ds_read_b128 v[210:213], v161 offset:56320
	global_load_lds_dwordx4 v130, s[98:99] offset:128
	s_add_i32 m0, s42, 0x1f80
	s_add_u32 s40, s40, 0x80080
	s_addc_u32 s41, s41, 0
	s_add_i32 s42, s67, s50
	global_load_lds_dwordx4 v134, s[98:99] offset:128
	s_mov_b32 m0, s42
	s_nop 0
	global_load_lds_dwordx4 v130, s[40:41]
	s_add_i32 m0, s42, 0x2000
	s_nop 0
	global_load_lds_dwordx4 v134, s[40:41]
	s_add_i32 m0, s56, 0xffffff80
	s_nop 0
	global_load_lds_dwordx4 v128, s[100:101] offset:128
	s_add_i32 m0, s57, 0xffffff80
	s_nop 0
	global_load_lds_dwordx4 v132, s[100:101] offset:128
	v_add_u32_e32 v254, 0x20000, v254
	v_and_b32_e32 v254, 0x1fffff, v254
	v_lshl_add_u64 v[250:251], v[254:255], 0, v[252:253]
	global_load_dword v249, v[250:251], off
	s_waitcnt vmcnt(9)
	s_waitcnt lgkmcnt(0)
	s_barrier
	s_setprio 1
	s_waitcnt lgkmcnt(0)
	v_mfma_f32_16x16x32_bf16 v[60:63], v[144:147], v[182:185], v[60:63]
	v_mfma_f32_16x16x32_bf16 v[56:59], v[152:155], v[182:185], v[56:59]
	v_mfma_f32_16x16x32_bf16 v[52:55], v[144:147], v[190:193], v[52:55]
	v_mfma_f32_16x16x32_bf16 v[44:47], v[152:155], v[190:193], v[44:47]
	v_mfma_f32_16x16x32_bf16 v[36:39], v[144:147], v[198:201], v[36:39]
	v_mfma_f32_16x16x32_bf16 v[28:31], v[152:155], v[198:201], v[28:31]
	v_mfma_f32_16x16x32_bf16 v[20:23], v[144:147], v[206:209], v[20:23]
	v_mfma_f32_16x16x32_bf16 v[8:11], v[152:155], v[206:209], v[8:11]
	v_mfma_f32_16x16x32_bf16 v[60:63], v[148:151], v[186:189], v[60:63]
	v_mfma_f32_16x16x32_bf16 v[56:59], v[162:165], v[186:189], v[56:59]
	v_mfma_f32_16x16x32_bf16 v[52:55], v[148:151], v[194:197], v[52:55]
	v_mfma_f32_16x16x32_bf16 v[44:47], v[162:165], v[194:197], v[44:47]
	v_mfma_f32_16x16x32_bf16 v[36:39], v[148:151], v[202:205], v[36:39]
	v_mfma_f32_16x16x32_bf16 v[28:31], v[162:165], v[202:205], v[28:31]
	v_mfma_f32_16x16x32_bf16 v[20:23], v[148:151], v[210:213], v[20:23]
	v_mfma_f32_16x16x32_bf16 v[8:11], v[162:165], v[210:213], v[8:11]
	s_setprio 0
	s_setprio 1
	v_mfma_f32_16x16x32_bf16 v[48:51], v[166:169], v[182:185], v[48:51]
	v_mfma_f32_16x16x32_bf16 v[40:43], v[174:177], v[182:185], v[40:43]
	v_mfma_f32_16x16x32_bf16 v[32:35], v[166:169], v[190:193], v[32:35]
	v_mfma_f32_16x16x32_bf16 v[24:27], v[174:177], v[190:193], v[24:27]
	v_mfma_f32_16x16x32_bf16 v[16:19], v[166:169], v[198:201], v[16:19]
	v_mfma_f32_16x16x32_bf16 v[12:15], v[174:177], v[198:201], v[12:15]
	v_mfma_f32_16x16x32_bf16 v[4:7], v[166:169], v[206:209], v[4:7]
	v_mfma_f32_16x16x32_bf16 v[0:3], v[174:177], v[206:209], v[0:3]
	v_mfma_f32_16x16x32_bf16 v[48:51], v[170:173], v[186:189], v[48:51]
	v_mfma_f32_16x16x32_bf16 v[40:43], v[178:181], v[186:189], v[40:43]
	v_mfma_f32_16x16x32_bf16 v[32:35], v[170:173], v[194:197], v[32:35]
	v_mfma_f32_16x16x32_bf16 v[24:27], v[178:181], v[194:197], v[24:27]
	v_mfma_f32_16x16x32_bf16 v[16:19], v[170:173], v[202:205], v[16:19]
	v_mfma_f32_16x16x32_bf16 v[12:15], v[178:181], v[202:205], v[12:15]
	v_mfma_f32_16x16x32_bf16 v[4:7], v[170:173], v[210:213], v[4:7]
	v_mfma_f32_16x16x32_bf16 v[0:3], v[178:181], v[210:213], v[0:3]
	s_setprio 0
	s_barrier
	s_add_i32 s65, s65, 2
	s_add_u32 s38, s38, 0x100
	s_addc_u32 s39, s39, 0
	s_add_u32 s63, s63, 0x100
	s_addc_u32 s64, s64, 0
	s_cmp_gt_u32 s65, 29
	s_cbranch_scc0 .LBB0_1946
	s_and_b64 vcc, exec, s[8:9]
	s_cbranch_vccz .LBB0_1949
	s_barrier
